# P3 gate-unit epilogue hand-rescheduled (sigmoids in place under load latency, ai=1 loads issued before ai=0 stores into freed accumulators, counted vmcnt); wave-groups re-aligned around P1/P3 epilogue
# speedup vs baseline: 1.0269x; 1.0269x over previous
.LBB0_90:
	s_and_b64 vcc, exec, s[6:7]
	s_cbranch_vccnz .LBB0_291
	s_cmpk_gt_u32 s2, 0xff
	s_cbranch_scc0 .Lal1_b
	s_barrier
.Lal1_b:
.LBB0_91:
	s_add_i32 s46, s46, 1
	s_mul_i32 s5, s46, s67
	s_mul_hi_u32 s6, s46, s66
	s_add_i32 s6, s6, s5
	s_mul_i32 s5, s46, s66
	s_add_u32 s20, s5, s65
	s_addc_u32 s21, s6, s64
	v_cmp_gt_i64_e64 s[6:7], s[20:21], v[194:195]
	s_mov_b64 s[0:1], s[12:13]
	s_mov_b64 s[8:9], s[14:15]
	s_mov_b32 s22, s10
	s_mov_b32 s23, s4
	s_and_b64 vcc, exec, s[6:7]
	s_cbranch_vccnz .LBB0_93
	s_ashr_i32 s4, s20, 31
	s_lshr_b32 s4, s4, 29
	s_add_i32 s4, s20, s4
	s_ashr_i32 s5, s4, 3
	s_and_b32 s4, s4, -8
	s_sub_i32 s4, s20, s4
	s_lshr_b32 s10, s4, 31
	s_addk_i32 s10, 0x303
	s_mul_i32 s4, s10, s4
	s_add_i32 s4, s4, s5
	s_mul_hi_i32 s5, s4, 0x2aaaaaab
	s_lshr_b32 s10, s5, 31
	s_ashr_i32 s5, s5, 5
	s_add_i32 s5, s5, s10
	s_lshl_b32 s11, s5, 3
	s_sub_i32 s10, 0x101, s11
	s_min_i32 s12, s10, 8
	s_abs_i32 s10, s12
	v_cvt_f32_u32_e32 v0, s10
	s_sub_i32 s14, 0, s10
	s_mulk_i32 s5, 0xc0
	s_sub_i32 s4, s4, s5
	v_rcp_iflag_f32_e32 v0, v0
	s_abs_i32 s5, s4
	s_xor_b32 s13, s4, s12
	s_ashr_i32 s13, s13, 31
	v_mul_f32_e32 v0, 0x4f7ffffe, v0
	v_cvt_u32_f32_e32 v0, v0
	v_readlane_b32 s48, v248, 49
	v_readlane_b32 s56, v248, 57
	v_readlane_b32 s57, v248, 58
	v_readfirstlane_b32 s15, v0
	s_mul_i32 s14, s14, s15
	s_mul_hi_u32 s14, s15, s14
	s_add_i32 s15, s15, s14
	s_mul_hi_u32 s14, s5, s15
	s_mul_i32 s15, s14, s10
	s_sub_i32 s5, s5, s15
	s_add_i32 s20, s14, 1
	s_sub_i32 s15, s5, s10
	s_cmp_ge_u32 s5, s10
	s_cselect_b32 s14, s20, s14
	s_cselect_b32 s5, s15, s5
	s_add_i32 s15, s14, 1
	s_cmp_ge_u32 s5, s10
	s_cselect_b32 s5, s15, s14
	s_xor_b32 s5, s5, s13
	s_sub_i32 s10, s5, s13
	s_mul_i32 s5, s10, s12
	s_sub_i32 s4, s4, s5
	s_add_i32 s4, s4, s11
	s_ashr_i32 s5, s4, 31
	s_lshl_b64 s[12:13], s[4:5], 19
	s_add_u32 s12, s56, s12
	s_addc_u32 s13, s57, s13
	s_ashr_i32 s11, s10, 31
	s_lshl_b64 s[14:15], s[10:11], 19
	s_add_u32 s14, s36, s14
	s_addc_u32 s15, s37, s15
	v_readlane_b32 s49, v248, 50
	v_readlane_b32 s50, v248, 51
	v_readlane_b32 s51, v248, 52
	v_readlane_b32 s52, v248, 53
	v_readlane_b32 s53, v248, 54
	v_readlane_b32 s54, v248, 55
	v_readlane_b32 s55, v248, 56
	v_readlane_b32 s58, v248, 59
	v_readlane_b32 s59, v248, 60
	v_readlane_b32 s60, v248, 61
	v_readlane_b32 s61, v248, 62
	v_readlane_b32 s62, v248, 63
	v_readlane_b32 s63, v247, 0

.LBB0_94:
	s_add_u32 s8, s0, 0xfffc0080
	s_addc_u32 s9, s1, -1
	s_cmp_eq_u32 s24, 12
	s_cselect_b32 s21, s13, s9
	s_cselect_b32 s20, s12, s8
	s_cselect_b32 s9, s15, s11
	s_cselect_b32 s8, s14, s5
	s_add_i32 s25, s89, 0x100
	v_add_u32_e32 v140, s25, v172
	ds_read_b128 v[128:131], v140
	ds_read_b128 v[132:135], v140 offset:1024
	ds_read_b128 v[136:139], v140 offset:2048
	ds_read_b128 v[140:143], v140 offset:3072
	v_lshl_add_u64 v[186:187], s[0:1], 0, v[156:157]
	s_add_i32 m0, s27, 0xc000
	ds_read_b128 v[144:147], v173
	ds_read_b128 v[148:151], v173 offset:1024
	ds_read_b128 v[160:163], v173 offset:2048
	ds_read_b128 v[164:167], v173 offset:3072
	ds_read_b128 v[168:171], v173 offset:4096
	ds_read_b128 v[174:177], v173 offset:5120
	ds_read_b128 v[178:181], v173 offset:6144
	ds_read_b128 v[182:185], v173 offset:7168
	global_load_lds_dwordx4 v[186:187], off
	v_lshl_add_u64 v[186:187], s[0:1], 0, v[158:159]
	s_add_i32 m0, s27, 0xe000
	s_nop 0
	global_load_lds_dwordx4 v[186:187], off
	s_waitcnt lgkmcnt(8)
	s_barrier
	s_waitcnt lgkmcnt(0)
	s_setprio 1
	s_waitcnt lgkmcnt(0)
	v_mfma_f32_16x16x32_bf16 v[124:127], v[128:131], v[144:147], v[124:127]
	v_mfma_f32_16x16x32_bf16 v[120:123], v[136:139], v[144:147], v[120:123]
	v_mfma_f32_16x16x32_bf16 v[108:111], v[128:131], v[160:163], v[108:111]
	v_mfma_f32_16x16x32_bf16 v[104:107], v[136:139], v[160:163], v[104:107]
	v_mfma_f32_16x16x32_bf16 v[92:95], v[128:131], v[168:171], v[92:95]
	v_mfma_f32_16x16x32_bf16 v[88:91], v[136:139], v[168:171], v[88:91]
	v_mfma_f32_16x16x32_bf16 v[76:79], v[128:131], v[178:181], v[76:79]
	v_mfma_f32_16x16x32_bf16 v[72:75], v[136:139], v[178:181], v[72:75]
	v_mfma_f32_16x16x32_bf16 v[124:127], v[132:135], v[148:151], v[124:127]
	v_mfma_f32_16x16x32_bf16 v[120:123], v[140:143], v[148:151], v[120:123]
	v_mfma_f32_16x16x32_bf16 v[108:111], v[132:135], v[164:167], v[108:111]
	v_mfma_f32_16x16x32_bf16 v[104:107], v[140:143], v[164:167], v[104:107]
	v_mfma_f32_16x16x32_bf16 v[92:95], v[132:135], v[174:177], v[92:95]
	v_mfma_f32_16x16x32_bf16 v[88:91], v[140:143], v[174:177], v[88:91]
	v_mfma_f32_16x16x32_bf16 v[76:79], v[132:135], v[182:185], v[76:79]
	v_mfma_f32_16x16x32_bf16 v[72:75], v[140:143], v[182:185], v[72:75]
	s_setprio 0
	s_barrier
	s_add_i32 s47, s90, 0x100
	v_add_u32_e32 v186, s47, v172
	s_add_i32 s25, s25, s3
	ds_read_b128 v[200:203], v186
	ds_read_b128 v[204:207], v186 offset:1024
	ds_read_b128 v[218:221], v186 offset:2048
	ds_read_b128 v[222:225], v186 offset:3072
	v_lshl_add_u64 v[186:187], s[8:9], 0, v[152:153]
	s_mov_b32 m0, s25
	v_lshl_add_u64 v[226:227], s[8:9], 0, v[154:155]
	global_load_lds_dwordx4 v[186:187], off
	s_add_i32 m0, s25, 0x2000
	s_nop 0
	global_load_lds_dwordx4 v[226:227], off
	s_barrier
	s_waitcnt lgkmcnt(0)
	s_setprio 1
	s_waitcnt lgkmcnt(0)
	v_mfma_f32_16x16x32_bf16 v[116:119], v[200:203], v[144:147], v[116:119]
	v_mfma_f32_16x16x32_bf16 v[112:115], v[218:221], v[144:147], v[112:115]
	v_mfma_f32_16x16x32_bf16 v[100:103], v[200:203], v[160:163], v[100:103]
	v_mfma_f32_16x16x32_bf16 v[96:99], v[218:221], v[160:163], v[96:99]
	v_mfma_f32_16x16x32_bf16 v[84:87], v[200:203], v[168:171], v[84:87]
	v_mfma_f32_16x16x32_bf16 v[80:83], v[218:221], v[168:171], v[80:83]
	v_mfma_f32_16x16x32_bf16 v[68:71], v[200:203], v[178:181], v[68:71]
	v_mfma_f32_16x16x32_bf16 v[64:67], v[218:221], v[178:181], v[64:67]
	v_mfma_f32_16x16x32_bf16 v[116:119], v[204:207], v[148:151], v[116:119]
	v_mfma_f32_16x16x32_bf16 v[112:115], v[222:225], v[148:151], v[112:115]
	v_mfma_f32_16x16x32_bf16 v[100:103], v[204:207], v[164:167], v[100:103]
	v_mfma_f32_16x16x32_bf16 v[96:99], v[222:225], v[164:167], v[96:99]
	v_mfma_f32_16x16x32_bf16 v[84:87], v[204:207], v[174:177], v[84:87]
	v_mfma_f32_16x16x32_bf16 v[80:83], v[222:225], v[174:177], v[80:83]
	v_mfma_f32_16x16x32_bf16 v[68:71], v[204:207], v[182:185], v[68:71]
	v_mfma_f32_16x16x32_bf16 v[64:67], v[222:225], v[182:185], v[64:67]
	s_setprio 0
	s_mov_b32 m0, s27
	v_lshl_add_u64 v[228:229], s[20:21], 0, v[152:153]
	s_barrier
	ds_read_b128 v[144:147], v173 offset:16384
	ds_read_b128 v[148:151], v173 offset:17408
	ds_read_b128 v[160:163], v173 offset:18432
	ds_read_b128 v[164:167], v173 offset:19456
	ds_read_b128 v[168:171], v173 offset:20480
	ds_read_b128 v[174:177], v173 offset:21504
	ds_read_b128 v[178:181], v173 offset:22528
	ds_read_b128 v[182:185], v173 offset:23552
	global_load_lds_dwordx4 v[228:229], off
	v_lshl_add_u64 v[230:231], s[20:21], 0, v[154:155]
	s_mov_b32 m0, s28
	s_nop 0
	global_load_lds_dwordx4 v[230:231], off
	s_barrier
	s_waitcnt lgkmcnt(0)
	s_setprio 1
	s_waitcnt lgkmcnt(0)
	v_mfma_f32_16x16x32_bf16 v[60:63], v[128:131], v[144:147], v[60:63]
	v_mfma_f32_16x16x32_bf16 v[56:59], v[136:139], v[144:147], v[56:59]
	v_mfma_f32_16x16x32_bf16 v[44:47], v[128:131], v[160:163], v[44:47]
	v_mfma_f32_16x16x32_bf16 v[40:43], v[136:139], v[160:163], v[40:43]
	v_mfma_f32_16x16x32_bf16 v[28:31], v[128:131], v[168:171], v[28:31]
	v_mfma_f32_16x16x32_bf16 v[24:27], v[136:139], v[168:171], v[24:27]
	v_mfma_f32_16x16x32_bf16 v[12:15], v[128:131], v[178:181], v[12:15]
	v_mfma_f32_16x16x32_bf16 v[8:11], v[136:139], v[178:181], v[8:11]
	v_mfma_f32_16x16x32_bf16 v[60:63], v[132:135], v[148:151], v[60:63]
	v_mfma_f32_16x16x32_bf16 v[56:59], v[140:143], v[148:151], v[56:59]
	v_mfma_f32_16x16x32_bf16 v[44:47], v[132:135], v[164:167], v[44:47]
	v_mfma_f32_16x16x32_bf16 v[40:43], v[140:143], v[164:167], v[40:43]
	v_mfma_f32_16x16x32_bf16 v[28:31], v[132:135], v[174:177], v[28:31]
	v_mfma_f32_16x16x32_bf16 v[24:27], v[140:143], v[174:177], v[24:27]
	v_mfma_f32_16x16x32_bf16 v[12:15], v[132:135], v[182:185], v[12:15]
	v_mfma_f32_16x16x32_bf16 v[8:11], v[140:143], v[182:185], v[8:11]
	s_setprio 0
	s_barrier
	s_add_u32 s48, s8, 0x40000
	s_addc_u32 s49, s9, 0
	s_add_i32 s25, s47, s3
	v_lshl_add_u64 v[128:129], s[48:49], 0, v[152:153]
	s_mov_b32 m0, s25
	s_nop 0
	global_load_lds_dwordx4 v[128:129], off
	v_lshl_add_u64 v[128:129], s[48:49], 0, v[154:155]
	s_add_i32 m0, s25, 0x2000
	s_nop 0
	global_load_lds_dwordx4 v[128:129], off
	s_waitcnt vmcnt(6)
	s_barrier
	s_setprio 1
	v_mfma_f32_16x16x32_bf16 v[52:55], v[200:203], v[144:147], v[52:55]
	v_mfma_f32_16x16x32_bf16 v[48:51], v[218:221], v[144:147], v[48:51]
	v_mfma_f32_16x16x32_bf16 v[36:39], v[200:203], v[160:163], v[36:39]
	v_mfma_f32_16x16x32_bf16 v[32:35], v[218:221], v[160:163], v[32:35]
	v_mfma_f32_16x16x32_bf16 v[20:23], v[200:203], v[168:171], v[20:23]
	v_mfma_f32_16x16x32_bf16 v[16:19], v[218:221], v[168:171], v[16:19]
	v_mfma_f32_16x16x32_bf16 v[4:7], v[200:203], v[178:181], v[4:7]
	v_mfma_f32_16x16x32_bf16 v[0:3], v[218:221], v[178:181], v[0:3]
	v_mfma_f32_16x16x32_bf16 v[52:55], v[204:207], v[148:151], v[52:55]
	v_mfma_f32_16x16x32_bf16 v[48:51], v[222:225], v[148:151], v[48:51]
	v_mfma_f32_16x16x32_bf16 v[36:39], v[204:207], v[164:167], v[36:39]
	v_mfma_f32_16x16x32_bf16 v[32:35], v[222:225], v[164:167], v[32:35]
	v_mfma_f32_16x16x32_bf16 v[20:23], v[204:207], v[174:177], v[20:23]
	v_mfma_f32_16x16x32_bf16 v[16:19], v[222:225], v[174:177], v[16:19]
	v_mfma_f32_16x16x32_bf16 v[4:7], v[204:207], v[182:185], v[4:7]
	v_mfma_f32_16x16x32_bf16 v[0:3], v[222:225], v[182:185], v[0:3]
	s_setprio 0
	s_add_i32 s25, s91, 0x100
	v_add_u32_e32 v140, s25, v172
	s_barrier
	ds_read_b128 v[128:131], v140
	ds_read_b128 v[132:135], v140 offset:1024
	ds_read_b128 v[136:139], v140 offset:2048
	ds_read_b128 v[140:143], v140 offset:3072
	s_add_u32 s20, s20, 0x40000
	s_addc_u32 s21, s21, 0
	s_mov_b32 m0, s29
	v_lshl_add_u64 v[200:201], s[20:21], 0, v[152:153]
	ds_read_b128 v[144:147], v173 offset:32768
	ds_read_b128 v[148:151], v173 offset:33792
	ds_read_b128 v[160:163], v173 offset:34816
	ds_read_b128 v[164:167], v173 offset:35840
	ds_read_b128 v[168:171], v173 offset:36864
	ds_read_b128 v[174:177], v173 offset:37888
	ds_read_b128 v[178:181], v173 offset:38912
	ds_read_b128 v[182:185], v173 offset:39936
	global_load_lds_dwordx4 v[200:201], off
	v_lshl_add_u64 v[200:201], s[20:21], 0, v[154:155]
	s_mov_b32 m0, s30
	s_nop 0
	global_load_lds_dwordx4 v[200:201], off
	s_waitcnt lgkmcnt(8)
	s_barrier
	s_waitcnt lgkmcnt(0)
	s_setprio 1
	s_waitcnt lgkmcnt(0)
	v_mfma_f32_16x16x32_bf16 v[124:127], v[128:131], v[144:147], v[124:127]
	v_mfma_f32_16x16x32_bf16 v[120:123], v[136:139], v[144:147], v[120:123]
	v_mfma_f32_16x16x32_bf16 v[108:111], v[128:131], v[160:163], v[108:111]
	v_mfma_f32_16x16x32_bf16 v[104:107], v[136:139], v[160:163], v[104:107]
	v_mfma_f32_16x16x32_bf16 v[92:95], v[128:131], v[168:171], v[92:95]
	v_mfma_f32_16x16x32_bf16 v[88:91], v[136:139], v[168:171], v[88:91]
	v_mfma_f32_16x16x32_bf16 v[76:79], v[128:131], v[178:181], v[76:79]
	v_mfma_f32_16x16x32_bf16 v[72:75], v[136:139], v[178:181], v[72:75]
	v_mfma_f32_16x16x32_bf16 v[124:127], v[132:135], v[148:151], v[124:127]
	v_mfma_f32_16x16x32_bf16 v[120:123], v[140:143], v[148:151], v[120:123]
	v_mfma_f32_16x16x32_bf16 v[108:111], v[132:135], v[164:167], v[108:111]
	v_mfma_f32_16x16x32_bf16 v[104:107], v[140:143], v[164:167], v[104:107]
	v_mfma_f32_16x16x32_bf16 v[92:95], v[132:135], v[174:177], v[92:95]
	v_mfma_f32_16x16x32_bf16 v[88:91], v[140:143], v[174:177], v[88:91]
	v_mfma_f32_16x16x32_bf16 v[76:79], v[132:135], v[182:185], v[76:79]
	v_mfma_f32_16x16x32_bf16 v[72:75], v[140:143], v[182:185], v[72:75]
	s_setprio 0
	s_barrier
	s_add_i32 s20, s94, 0x100
	s_add_i32 s21, s25, s3
	v_add_u32_e32 v190, s20, v172
	v_lshl_add_u64 v[186:187], v[186:187], 0, s[96:97]
	s_mov_b32 m0, s21
	ds_read_b128 v[200:203], v190
	ds_read_b128 v[204:207], v190 offset:1024
	ds_read_b128 v[218:221], v190 offset:2048
	ds_read_b128 v[222:225], v190 offset:3072
	global_load_lds_dwordx4 v[186:187], off
	v_lshl_add_u64 v[186:187], v[226:227], 0, s[96:97]
	s_add_i32 m0, s21, 0x2000
	s_nop 0
	global_load_lds_dwordx4 v[186:187], off
	s_barrier
	s_waitcnt lgkmcnt(0)
	s_setprio 1
	s_waitcnt lgkmcnt(0)
	v_mfma_f32_16x16x32_bf16 v[116:119], v[200:203], v[144:147], v[116:119]
	v_mfma_f32_16x16x32_bf16 v[112:115], v[218:221], v[144:147], v[112:115]
	v_mfma_f32_16x16x32_bf16 v[100:103], v[200:203], v[160:163], v[100:103]
	v_mfma_f32_16x16x32_bf16 v[96:99], v[218:221], v[160:163], v[96:99]
	v_mfma_f32_16x16x32_bf16 v[84:87], v[200:203], v[168:171], v[84:87]
	v_mfma_f32_16x16x32_bf16 v[80:83], v[218:221], v[168:171], v[80:83]
	v_mfma_f32_16x16x32_bf16 v[68:71], v[200:203], v[178:181], v[68:71]
	v_mfma_f32_16x16x32_bf16 v[64:67], v[218:221], v[178:181], v[64:67]
	v_mfma_f32_16x16x32_bf16 v[116:119], v[204:207], v[148:151], v[116:119]
	v_mfma_f32_16x16x32_bf16 v[112:115], v[222:225], v[148:151], v[112:115]
	v_mfma_f32_16x16x32_bf16 v[100:103], v[204:207], v[164:167], v[100:103]
	v_mfma_f32_16x16x32_bf16 v[96:99], v[222:225], v[164:167], v[96:99]
	v_mfma_f32_16x16x32_bf16 v[84:87], v[204:207], v[174:177], v[84:87]
	v_mfma_f32_16x16x32_bf16 v[80:83], v[222:225], v[174:177], v[80:83]
	v_mfma_f32_16x16x32_bf16 v[68:71], v[204:207], v[182:185], v[68:71]
	v_mfma_f32_16x16x32_bf16 v[64:67], v[222:225], v[182:185], v[64:67]
	s_setprio 0
	s_mov_b32 m0, s31
	v_lshl_add_u64 v[186:187], v[228:229], 0, s[96:97]
	s_barrier
	ds_read_b128 v[144:147], v173 offset:49152
	ds_read_b128 v[148:151], v173 offset:50176
	ds_read_b128 v[160:163], v173 offset:51200
	ds_read_b128 v[164:167], v173 offset:52224
	ds_read_b128 v[168:171], v173 offset:53248
	ds_read_b128 v[174:177], v173 offset:54272
	ds_read_b128 v[178:181], v173 offset:55296
	ds_read_b128 v[182:185], v173 offset:56320
	global_load_lds_dwordx4 v[186:187], off
	v_lshl_add_u64 v[186:187], v[230:231], 0, s[96:97]
	s_mov_b32 m0, s34
	s_nop 0
	global_load_lds_dwordx4 v[186:187], off
	s_barrier
	s_waitcnt lgkmcnt(0)
	s_setprio 1
	s_waitcnt lgkmcnt(0)
	v_mfma_f32_16x16x32_bf16 v[60:63], v[128:131], v[144:147], v[60:63]
	v_mfma_f32_16x16x32_bf16 v[56:59], v[136:139], v[144:147], v[56:59]
	v_mfma_f32_16x16x32_bf16 v[44:47], v[128:131], v[160:163], v[44:47]
	v_mfma_f32_16x16x32_bf16 v[40:43], v[136:139], v[160:163], v[40:43]
	v_mfma_f32_16x16x32_bf16 v[28:31], v[128:131], v[168:171], v[28:31]
	v_mfma_f32_16x16x32_bf16 v[24:27], v[136:139], v[168:171], v[24:27]
	v_mfma_f32_16x16x32_bf16 v[12:15], v[128:131], v[178:181], v[12:15]
	v_mfma_f32_16x16x32_bf16 v[8:11], v[136:139], v[178:181], v[8:11]
	v_mfma_f32_16x16x32_bf16 v[60:63], v[132:135], v[148:151], v[60:63]
	v_mfma_f32_16x16x32_bf16 v[56:59], v[140:143], v[148:151], v[56:59]
	v_mfma_f32_16x16x32_bf16 v[44:47], v[132:135], v[164:167], v[44:47]
	v_mfma_f32_16x16x32_bf16 v[40:43], v[140:143], v[164:167], v[40:43]
	v_mfma_f32_16x16x32_bf16 v[28:31], v[132:135], v[174:177], v[28:31]
	v_mfma_f32_16x16x32_bf16 v[24:27], v[140:143], v[174:177], v[24:27]
	v_mfma_f32_16x16x32_bf16 v[12:15], v[132:135], v[182:185], v[12:15]
	v_mfma_f32_16x16x32_bf16 v[8:11], v[140:143], v[182:185], v[8:11]
	s_setprio 0
	s_barrier
	s_add_u32 s8, s8, 0x40080
	s_addc_u32 s9, s9, 0
	s_add_i32 s20, s20, s3
	v_lshl_add_u64 v[128:129], s[8:9], 0, v[152:153]
	s_mov_b32 m0, s20
	s_nop 0
	global_load_lds_dwordx4 v[128:129], off
	v_lshl_add_u64 v[128:129], s[8:9], 0, v[154:155]
	s_add_i32 m0, s20, 0x2000
	s_nop 0
	global_load_lds_dwordx4 v[128:129], off
	s_waitcnt vmcnt(6)
	s_barrier
	s_setprio 1
	v_mfma_f32_16x16x32_bf16 v[52:55], v[200:203], v[144:147], v[52:55]
	v_mfma_f32_16x16x32_bf16 v[48:51], v[218:221], v[144:147], v[48:51]
	v_mfma_f32_16x16x32_bf16 v[36:39], v[200:203], v[160:163], v[36:39]
	v_mfma_f32_16x16x32_bf16 v[32:35], v[218:221], v[160:163], v[32:35]
	v_mfma_f32_16x16x32_bf16 v[20:23], v[200:203], v[168:171], v[20:23]
	v_mfma_f32_16x16x32_bf16 v[16:19], v[218:221], v[168:171], v[16:19]
	v_mfma_f32_16x16x32_bf16 v[4:7], v[200:203], v[178:181], v[4:7]
	v_mfma_f32_16x16x32_bf16 v[0:3], v[218:221], v[178:181], v[0:3]
	v_mfma_f32_16x16x32_bf16 v[52:55], v[204:207], v[148:151], v[52:55]
	v_mfma_f32_16x16x32_bf16 v[48:51], v[222:225], v[148:151], v[48:51]
	v_mfma_f32_16x16x32_bf16 v[36:39], v[204:207], v[164:167], v[36:39]
	v_mfma_f32_16x16x32_bf16 v[32:35], v[222:225], v[164:167], v[32:35]
	v_mfma_f32_16x16x32_bf16 v[20:23], v[204:207], v[174:177], v[20:23]
	v_mfma_f32_16x16x32_bf16 v[16:19], v[222:225], v[174:177], v[16:19]
	v_mfma_f32_16x16x32_bf16 v[4:7], v[204:207], v[182:185], v[4:7]
	v_mfma_f32_16x16x32_bf16 v[0:3], v[222:225], v[182:185], v[0:3]
	s_setprio 0
	s_add_i32 s24, s24, 2
	s_add_u32 s0, s0, 0x100
	s_addc_u32 s1, s1, 0
	s_add_u32 s5, s5, 0x100
	s_addc_u32 s11, s11, 0
	s_cmp_gt_u32 s24, 13
	s_barrier
	s_cbranch_scc0 .LBB0_94
	s_cmpk_gt_u32 s2, 0xff
	s_cbranch_scc1 .Lal1_a
	s_barrier
.Lal1_a:
	v_mov_b32_e32 v128, v188
	s_lshl_b32 s1, s23, 8
	v_readfirstlane_b32 s0, v128
	s_bfe_u32 s5, s0, 0x20006
	s_ashr_i32 s0, s0, 2
	s_andn2_b32 s0, s0, 63
	s_add_i32 s0, s0, s1
	v_bfe_u32 v174, v128, 4, 2
	v_and_or_b32 v160, v128, 15, s0
	s_cmp_gt_i32 s22, 7
	s_mov_b64 s[0:1], -1
	s_cbranch_scc0 .LBB0_207
	s_cmp_gt_u32 s22, 15
	s_cbranch_scc0 .LBB0_169
	s_lshl_b32 s0, s22, 2
	s_and_b32 s0, s0, 4
	s_add_i32 s8, s22, -16
	s_or_b32 s0, s5, s0
	s_lshr_b32 s11, s8, 1
	s_lshl_b32 s0, s0, 6
	v_lshlrev_b32_e32 v130, 2, v174
	v_lshlrev_b32_e32 v131, 3, v174
	v_or_b32_e32 v164, s0, v130
	v_or_b32_e32 v162, s0, v131
	s_cmp_gt_u32 s8, 3
	s_mov_b64 s[0:1], -1
	s_cbranch_scc0 .LBB0_103
	s_cmp_eq_u32 s11, 2
	s_cbranch_scc1 .LBB0_100
	v_mul_f32_e32 v133, 0xbfb8aa3b, v120
	v_mul_f32_e32 v134, 0xbfb8aa3b, v125
	v_exp_f32_e32 v133, v133
	v_exp_f32_e32 v134, v134
	v_mul_f32_e32 v135, 0xbfb8aa3b, v121
	v_exp_f32_e32 v135, v135
	v_add_f32_e32 v133, 1.0, v133
	v_add_f32_e32 v134, 1.0, v134
	v_rcp_f32_e32 v133, v133
	v_rcp_f32_e32 v134, v134
	v_mul_f32_e32 v132, 0xbfb8aa3b, v124
	v_exp_f32_e32 v132, v132
	v_mul_f32_e32 v136, v120, v133
	v_mul_f32_e32 v133, v125, v134
	v_add_f32_e32 v134, 1.0, v135
	v_mul_f32_e32 v135, 0xbfb8aa3b, v126
	v_exp_f32_e32 v135, v135
	v_mul_f32_e32 v138, 0xbfb8aa3b, v127
	v_mul_f32_e32 v137, 0xbfb8aa3b, v122
	v_exp_f32_e32 v138, v138
	v_mul_f32_e32 v139, 0xbfb8aa3b, v123
	v_exp_f32_e32 v137, v137
	v_exp_f32_e32 v139, v139
	v_add_f32_e32 v132, 1.0, v132
	v_add_f32_e32 v135, 1.0, v135
	v_rcp_f32_e32 v132, v132
	v_rcp_f32_e32 v134, v134
	v_rcp_f32_e32 v135, v135
	v_add_f32_e32 v138, 1.0, v138
	v_add_f32_e32 v137, 1.0, v137
	v_rcp_f32_e32 v138, v138
	v_add_f32_e32 v139, 1.0, v139
	v_ashrrev_i32_e32 v161, 31, v160
	v_readlane_b32 s48, v247, 7
	v_rcp_f32_e32 v137, v137
	v_rcp_f32_e32 v139, v139
	v_lshlrev_b64 v[128:129], 10, v[160:161]
	v_readlane_b32 s54, v247, 13
	v_readlane_b32 s55, v247, 14
	v_lshlrev_b32_e32 v190, 1, v162
	v_mul_f32_e32 v132, v124, v132
	v_lshl_add_u64 v[128:129], s[54:55], 0, v[128:129]
	v_mul_f32_e32 v134, v121, v134
	v_mul_f32_e32 v135, v126, v135
	v_lshl_add_u64 v[128:129], v[128:129], 0, v[190:191]
	v_mul_f32_e32 v138, v127, v138
	v_cvt_pk_bf16_f32 v132, v132, v133
	v_cvt_pk_bf16_f32 v133, v135, v138
	v_mul_f32_e32 v135, 0xbfb8aa3b, v116
	v_cvt_pk_bf16_f32 v134, v136, v134
	v_mul_f32_e32 v137, v122, v137
	v_mul_f32_e32 v139, v123, v139
	v_exp_f32_e32 v138, v135
	v_cvt_pk_bf16_f32 v135, v137, v139
	global_store_dwordx4 v[128:129], v[132:135], off
	v_mul_f32_e32 v137, 0xbfb8aa3b, v114
	v_mul_f32_e32 v139, 0xbfb8aa3b, v115
	v_mul_f32_e32 v133, 0xbfb8aa3b, v112
	v_mul_f32_e32 v134, 0xbfb8aa3b, v117
	v_exp_f32_e32 v133, v133
	v_exp_f32_e32 v134, v134
	v_mul_f32_e32 v135, 0xbfb8aa3b, v113
	v_exp_f32_e32 v135, v135
	v_add_f32_e32 v133, 1.0, v133
	v_add_f32_e32 v134, 1.0, v134
	v_rcp_f32_e32 v133, v133
	v_rcp_f32_e32 v134, v134
	v_add_f32_e32 v132, 1.0, v138
	v_mul_f32_e32 v138, 0xbfb8aa3b, v119
	v_mul_f32_e32 v136, v112, v133
	v_mul_f32_e32 v133, v117, v134
	v_add_f32_e32 v134, 1.0, v135
	v_mul_f32_e32 v135, 0xbfb8aa3b, v118
	v_exp_f32_e32 v135, v135
	v_exp_f32_e32 v138, v138
	v_exp_f32_e32 v137, v137
	v_exp_f32_e32 v139, v139
	v_add_f32_e32 v135, 1.0, v135
	v_rcp_f32_e32 v132, v132
	v_rcp_f32_e32 v134, v134
	v_rcp_f32_e32 v135, v135
	v_add_f32_e32 v138, 1.0, v138
	v_add_f32_e32 v137, 1.0, v137
	v_rcp_f32_e32 v138, v138
	v_add_f32_e32 v139, 1.0, v139
	v_rcp_f32_e32 v137, v137
	v_rcp_f32_e32 v139, v139
	v_mul_f32_e32 v132, v116, v132
	v_mul_f32_e32 v134, v113, v134
	v_mul_f32_e32 v135, v118, v135
	v_mul_f32_e32 v138, v119, v138
	v_cvt_pk_bf16_f32 v132, v132, v133
	v_cvt_pk_bf16_f32 v133, v135, v138
	v_cvt_pk_bf16_f32 v134, v136, v134
	v_mul_f32_e32 v135, 0xbfb8aa3b, v108
	v_mul_f32_e32 v137, v114, v137
	v_mul_f32_e32 v139, v115, v139
	v_exp_f32_e32 v138, v135
	v_cvt_pk_bf16_f32 v135, v137, v139
	global_store_dwordx4 v[128:129], v[132:135], off offset:64
	v_mul_f32_e32 v140, 0xbfb8aa3b, v111
	v_mul_f32_e32 v139, 0xbfb8aa3b, v106
	v_mul_f32_e32 v133, 0xbfb8aa3b, v104
	v_mul_f32_e32 v134, 0xbfb8aa3b, v109
	v_exp_f32_e32 v133, v133
	v_exp_f32_e32 v134, v134
	v_mul_f32_e32 v135, 0xbfb8aa3b, v105
	v_exp_f32_e32 v135, v135
	v_add_f32_e32 v133, 1.0, v133
	v_add_f32_e32 v134, 1.0, v134
	v_rcp_f32_e32 v133, v133
	v_rcp_f32_e32 v134, v134
	v_add_f32_e32 v132, 1.0, v138
	v_exp_f32_e32 v140, v140
	v_mul_f32_e32 v138, v104, v133
	v_mul_f32_e32 v133, v109, v134
	v_add_f32_e32 v134, 1.0, v135
	v_mul_f32_e32 v135, 0xbfb8aa3b, v110
	v_exp_f32_e32 v135, v135
	v_exp_f32_e32 v139, v139
	v_mul_f32_e32 v141, 0xbfb8aa3b, v107
	v_exp_f32_e32 v141, v141
	v_rcp_f32_e32 v132, v132
	v_rcp_f32_e32 v134, v134
	v_add_f32_e32 v135, 1.0, v135
	v_add_f32_e32 v140, 1.0, v140
	v_rcp_f32_e32 v135, v135
	v_add_f32_e32 v139, 1.0, v139
	v_rcp_f32_e32 v140, v140
	v_rcp_f32_e32 v139, v139
	v_add_f32_e32 v141, 1.0, v141
	v_rcp_f32_e32 v141, v141
	s_mov_b64 s[0:1], 0x4000
	v_mul_f32_e32 v132, v108, v132
	v_mul_f32_e32 v134, v105, v134
	v_lshl_add_u64 v[136:137], v[128:129], 0, s[0:1]
	v_mul_f32_e32 v135, v110, v135
	v_mul_f32_e32 v140, v111, v140
	v_cvt_pk_bf16_f32 v132, v132, v133
	v_cvt_pk_bf16_f32 v133, v135, v140
	v_cvt_pk_bf16_f32 v134, v138, v134
	v_mul_f32_e32 v138, 0xbfb8aa3b, v100
	s_movk_i32 s0, 0x4000
	v_mul_f32_e32 v139, v106, v139
	v_exp_f32_e32 v140, v138
	v_add_co_u32_e32 v138, vcc, s0, v128
	v_mul_f32_e32 v141, v107, v141
	v_cvt_pk_bf16_f32 v135, v139, v141
	s_nop 0
	v_addc_co_u32_e32 v139, vcc, 0, v129, vcc
	global_store_dwordx4 v[138:139], v[132:135], off
	v_mul_f32_e32 v139, 0xbfb8aa3b, v98
	v_mul_f32_e32 v141, 0xbfb8aa3b, v99
	v_mul_f32_e32 v133, 0xbfb8aa3b, v96
	v_mul_f32_e32 v134, 0xbfb8aa3b, v101
	v_exp_f32_e32 v133, v133
	v_exp_f32_e32 v134, v134
	v_mul_f32_e32 v135, 0xbfb8aa3b, v97
	v_exp_f32_e32 v135, v135
	v_add_f32_e32 v133, 1.0, v133
	v_add_f32_e32 v134, 1.0, v134
	v_rcp_f32_e32 v133, v133
	v_rcp_f32_e32 v134, v134
	v_add_f32_e32 v132, 1.0, v140
	v_mul_f32_e32 v140, 0xbfb8aa3b, v103
	v_mul_f32_e32 v138, v96, v133
	v_mul_f32_e32 v133, v101, v134
	v_add_f32_e32 v134, 1.0, v135
	v_mul_f32_e32 v135, 0xbfb8aa3b, v102
	v_exp_f32_e32 v135, v135
	v_exp_f32_e32 v140, v140
	v_exp_f32_e32 v139, v139
	v_exp_f32_e32 v141, v141
	v_add_f32_e32 v135, 1.0, v135
	v_rcp_f32_e32 v132, v132
	v_rcp_f32_e32 v134, v134
	v_rcp_f32_e32 v135, v135
	v_add_f32_e32 v140, 1.0, v140
	v_add_f32_e32 v139, 1.0, v139
	v_rcp_f32_e32 v140, v140
	v_add_f32_e32 v141, 1.0, v141
	v_rcp_f32_e32 v139, v139
	v_rcp_f32_e32 v141, v141
	v_mul_f32_e32 v132, v100, v132
	v_mul_f32_e32 v134, v97, v134
	v_mul_f32_e32 v135, v102, v135
	v_mul_f32_e32 v140, v103, v140
	v_cvt_pk_bf16_f32 v132, v132, v133
	v_cvt_pk_bf16_f32 v133, v135, v140
	v_cvt_pk_bf16_f32 v134, v138, v134
	v_mul_f32_e32 v135, 0xbfb8aa3b, v92
	v_mul_f32_e32 v139, v98, v139
	v_mul_f32_e32 v141, v99, v141
	v_exp_f32_e32 v138, v135
	v_cvt_pk_bf16_f32 v135, v139, v141
	global_store_dwordx4 v[136:137], v[132:135], off offset:64
	v_mul_f32_e32 v140, 0xbfb8aa3b, v95
	v_mul_f32_e32 v139, 0xbfb8aa3b, v90
	v_mul_f32_e32 v133, 0xbfb8aa3b, v88
	v_mul_f32_e32 v134, 0xbfb8aa3b, v93
	v_exp_f32_e32 v133, v133
	v_exp_f32_e32 v134, v134
	v_mul_f32_e32 v135, 0xbfb8aa3b, v89
	v_exp_f32_e32 v135, v135
	v_add_f32_e32 v133, 1.0, v133
	v_add_f32_e32 v134, 1.0, v134
	v_rcp_f32_e32 v133, v133
	v_rcp_f32_e32 v134, v134
	v_add_f32_e32 v132, 1.0, v138
	v_exp_f32_e32 v140, v140
	v_mul_f32_e32 v138, v88, v133
	v_mul_f32_e32 v133, v93, v134
	v_add_f32_e32 v134, 1.0, v135
	v_mul_f32_e32 v135, 0xbfb8aa3b, v94
	v_exp_f32_e32 v135, v135
	v_exp_f32_e32 v139, v139
	v_mul_f32_e32 v141, 0xbfb8aa3b, v91
	v_exp_f32_e32 v141, v141
	v_rcp_f32_e32 v132, v132
	v_rcp_f32_e32 v134, v134
	v_add_f32_e32 v135, 1.0, v135
	v_add_f32_e32 v140, 1.0, v140
	v_rcp_f32_e32 v135, v135
	v_add_f32_e32 v139, 1.0, v139
	v_rcp_f32_e32 v140, v140
	v_rcp_f32_e32 v139, v139
	v_add_f32_e32 v141, 1.0, v141
	v_rcp_f32_e32 v141, v141
	s_mov_b64 s[0:1], 0x8000
	v_mul_f32_e32 v132, v92, v132
	v_mul_f32_e32 v134, v89, v134
	v_lshl_add_u64 v[136:137], v[128:129], 0, s[0:1]
	v_mul_f32_e32 v135, v94, v135
	v_mul_f32_e32 v140, v95, v140
	v_cvt_pk_bf16_f32 v132, v132, v133
	v_cvt_pk_bf16_f32 v133, v135, v140
	v_cvt_pk_bf16_f32 v134, v138, v134
	v_mul_f32_e32 v138, 0xbfb8aa3b, v84
	s_mov_b32 s0, 0x8000
	v_mul_f32_e32 v139, v90, v139
	v_exp_f32_e32 v140, v138
	v_add_co_u32_e32 v138, vcc, s0, v128
	v_mul_f32_e32 v141, v91, v141
	v_cvt_pk_bf16_f32 v135, v139, v141
	s_nop 0
	v_addc_co_u32_e32 v139, vcc, 0, v129, vcc
	global_store_dwordx4 v[138:139], v[132:135], off
	v_mul_f32_e32 v139, 0xbfb8aa3b, v82
	v_mul_f32_e32 v141, 0xbfb8aa3b, v83
	v_mul_f32_e32 v133, 0xbfb8aa3b, v80
	v_mul_f32_e32 v134, 0xbfb8aa3b, v85
	v_exp_f32_e32 v133, v133
	v_exp_f32_e32 v134, v134
	v_mul_f32_e32 v135, 0xbfb8aa3b, v81
	v_exp_f32_e32 v135, v135
	v_add_f32_e32 v133, 1.0, v133
	v_add_f32_e32 v134, 1.0, v134
	v_rcp_f32_e32 v133, v133
	v_rcp_f32_e32 v134, v134
	v_add_f32_e32 v132, 1.0, v140
	v_mul_f32_e32 v140, 0xbfb8aa3b, v87
	v_mul_f32_e32 v138, v80, v133
	v_mul_f32_e32 v133, v85, v134
	v_add_f32_e32 v134, 1.0, v135
	v_mul_f32_e32 v135, 0xbfb8aa3b, v86
	v_exp_f32_e32 v135, v135
	v_exp_f32_e32 v140, v140
	v_exp_f32_e32 v139, v139
	v_exp_f32_e32 v141, v141
	v_add_f32_e32 v135, 1.0, v135
	v_rcp_f32_e32 v132, v132
	v_rcp_f32_e32 v134, v134
	v_rcp_f32_e32 v135, v135
	v_add_f32_e32 v140, 1.0, v140
	v_add_f32_e32 v139, 1.0, v139
	v_rcp_f32_e32 v140, v140
	v_add_f32_e32 v141, 1.0, v141
	v_rcp_f32_e32 v139, v139
	v_rcp_f32_e32 v141, v141
	v_mul_f32_e32 v132, v84, v132
	v_mul_f32_e32 v134, v81, v134
	v_mul_f32_e32 v135, v86, v135
	v_mul_f32_e32 v140, v87, v140
	v_cvt_pk_bf16_f32 v132, v132, v133
	v_cvt_pk_bf16_f32 v133, v135, v140
	v_cvt_pk_bf16_f32 v134, v138, v134
	v_mul_f32_e32 v135, 0xbfb8aa3b, v76
	v_mul_f32_e32 v139, v82, v139
	v_mul_f32_e32 v141, v83, v141
	v_exp_f32_e32 v138, v135
	v_cvt_pk_bf16_f32 v135, v139, v141
	global_store_dwordx4 v[136:137], v[132:135], off offset:64
	v_mul_f32_e32 v140, 0xbfb8aa3b, v79
	v_mul_f32_e32 v139, 0xbfb8aa3b, v74
	v_mul_f32_e32 v133, 0xbfb8aa3b, v72
	v_mul_f32_e32 v134, 0xbfb8aa3b, v77
	v_exp_f32_e32 v133, v133
	v_exp_f32_e32 v134, v134
	v_mul_f32_e32 v135, 0xbfb8aa3b, v73
	v_exp_f32_e32 v135, v135
	v_add_f32_e32 v133, 1.0, v133
	v_add_f32_e32 v134, 1.0, v134
	v_rcp_f32_e32 v133, v133
	v_rcp_f32_e32 v134, v134
	v_add_f32_e32 v132, 1.0, v138
	v_exp_f32_e32 v140, v140
	v_mul_f32_e32 v138, v72, v133
	v_mul_f32_e32 v133, v77, v134
	v_add_f32_e32 v134, 1.0, v135
	v_mul_f32_e32 v135, 0xbfb8aa3b, v78
	v_exp_f32_e32 v135, v135
	v_exp_f32_e32 v139, v139
	v_mul_f32_e32 v141, 0xbfb8aa3b, v75
	v_exp_f32_e32 v141, v141
	v_rcp_f32_e32 v132, v132
	v_rcp_f32_e32 v134, v134
	v_add_f32_e32 v135, 1.0, v135
	v_add_f32_e32 v140, 1.0, v140
	v_rcp_f32_e32 v135, v135
	v_add_f32_e32 v139, 1.0, v139
	v_rcp_f32_e32 v140, v140
	v_rcp_f32_e32 v139, v139
	v_add_f32_e32 v141, 1.0, v141
	v_rcp_f32_e32 v141, v141
	s_mov_b64 s[0:1], 0xc000
	v_mul_f32_e32 v132, v76, v132
	v_mul_f32_e32 v134, v73, v134
	v_lshl_add_u64 v[136:137], v[128:129], 0, s[0:1]
	v_mul_f32_e32 v135, v78, v135
	v_mul_f32_e32 v140, v79, v140
	v_cvt_pk_bf16_f32 v132, v132, v133
	v_cvt_pk_bf16_f32 v133, v135, v140
	v_cvt_pk_bf16_f32 v134, v138, v134
	v_mul_f32_e32 v138, 0xbfb8aa3b, v68
	s_mov_b32 s0, 0xc000
	v_mul_f32_e32 v139, v74, v139
	v_exp_f32_e32 v140, v138
	v_add_co_u32_e32 v138, vcc, s0, v128
	v_mul_f32_e32 v141, v75, v141
	v_cvt_pk_bf16_f32 v135, v139, v141
	s_nop 0
	v_addc_co_u32_e32 v139, vcc, 0, v129, vcc
	global_store_dwordx4 v[138:139], v[132:135], off
	v_mul_f32_e32 v139, 0xbfb8aa3b, v66
	v_mul_f32_e32 v141, 0xbfb8aa3b, v67
	v_mul_f32_e32 v133, 0xbfb8aa3b, v64
	v_mul_f32_e32 v134, 0xbfb8aa3b, v69
	v_exp_f32_e32 v133, v133
	v_exp_f32_e32 v134, v134
	v_mul_f32_e32 v135, 0xbfb8aa3b, v65
	v_exp_f32_e32 v135, v135
	v_add_f32_e32 v133, 1.0, v133
	v_add_f32_e32 v134, 1.0, v134
	v_rcp_f32_e32 v133, v133
	v_rcp_f32_e32 v134, v134
	v_add_f32_e32 v132, 1.0, v140
	v_mul_f32_e32 v140, 0xbfb8aa3b, v71
	v_mul_f32_e32 v138, v64, v133
	v_mul_f32_e32 v133, v69, v134
	v_add_f32_e32 v134, 1.0, v135
	v_mul_f32_e32 v135, 0xbfb8aa3b, v70
	v_exp_f32_e32 v135, v135
	v_exp_f32_e32 v140, v140
	v_exp_f32_e32 v139, v139
	v_exp_f32_e32 v141, v141
	v_add_f32_e32 v135, 1.0, v135
	v_rcp_f32_e32 v132, v132
	v_rcp_f32_e32 v134, v134
	v_rcp_f32_e32 v135, v135
	v_add_f32_e32 v140, 1.0, v140
	v_add_f32_e32 v139, 1.0, v139
	v_rcp_f32_e32 v140, v140
	v_add_f32_e32 v141, 1.0, v141
	v_rcp_f32_e32 v139, v139
	v_rcp_f32_e32 v141, v141
	v_mul_f32_e32 v132, v68, v132
	v_mul_f32_e32 v134, v65, v134
	v_mul_f32_e32 v135, v70, v135
	v_mul_f32_e32 v140, v71, v140
	v_cvt_pk_bf16_f32 v132, v132, v133
	v_cvt_pk_bf16_f32 v133, v135, v140
	v_cvt_pk_bf16_f32 v134, v138, v134
	v_mul_f32_e32 v135, 0xbfb8aa3b, v60
	v_mul_f32_e32 v139, v66, v139
	v_mul_f32_e32 v141, v67, v141
	v_exp_f32_e32 v138, v135
	v_cvt_pk_bf16_f32 v135, v139, v141
	global_store_dwordx4 v[136:137], v[132:135], off offset:64
	v_mul_f32_e32 v140, 0xbfb8aa3b, v63
	v_mul_f32_e32 v139, 0xbfb8aa3b, v58
	v_mul_f32_e32 v133, 0xbfb8aa3b, v56
	v_mul_f32_e32 v134, 0xbfb8aa3b, v61
	v_exp_f32_e32 v133, v133
	v_exp_f32_e32 v134, v134
	v_mul_f32_e32 v135, 0xbfb8aa3b, v57
	v_exp_f32_e32 v135, v135
	v_add_f32_e32 v133, 1.0, v133
	v_add_f32_e32 v134, 1.0, v134
	v_rcp_f32_e32 v133, v133
	v_rcp_f32_e32 v134, v134
	v_add_f32_e32 v132, 1.0, v138
	v_exp_f32_e32 v140, v140
	v_mul_f32_e32 v138, v56, v133
	v_mul_f32_e32 v133, v61, v134
	v_add_f32_e32 v134, 1.0, v135
	v_mul_f32_e32 v135, 0xbfb8aa3b, v62
	v_exp_f32_e32 v135, v135
	v_exp_f32_e32 v139, v139
	v_mul_f32_e32 v141, 0xbfb8aa3b, v59
	v_exp_f32_e32 v141, v141
	v_rcp_f32_e32 v132, v132
	v_rcp_f32_e32 v134, v134
	v_add_f32_e32 v135, 1.0, v135
	v_add_f32_e32 v140, 1.0, v140
	v_rcp_f32_e32 v135, v135
	v_add_f32_e32 v139, 1.0, v139
	v_rcp_f32_e32 v140, v140
	v_rcp_f32_e32 v139, v139
	v_add_f32_e32 v141, 1.0, v141
	v_rcp_f32_e32 v141, v141
	s_mov_b64 s[0:1], 0x20000
	v_mul_f32_e32 v132, v60, v132
	v_mul_f32_e32 v134, v57, v134
	v_lshl_add_u64 v[136:137], v[128:129], 0, s[0:1]
	v_mul_f32_e32 v135, v62, v135
	v_mul_f32_e32 v140, v63, v140
	v_cvt_pk_bf16_f32 v132, v132, v133
	v_cvt_pk_bf16_f32 v133, v135, v140
	v_cvt_pk_bf16_f32 v134, v138, v134
	v_mul_f32_e32 v138, 0xbfb8aa3b, v52
	s_mov_b32 s0, 0x20000
	v_mul_f32_e32 v139, v58, v139
	v_exp_f32_e32 v140, v138
	v_add_co_u32_e32 v138, vcc, s0, v128
	v_mul_f32_e32 v141, v59, v141
	v_cvt_pk_bf16_f32 v135, v139, v141
	s_nop 0
	v_addc_co_u32_e32 v139, vcc, 0, v129, vcc
	global_store_dwordx4 v[138:139], v[132:135], off
	v_mul_f32_e32 v139, 0xbfb8aa3b, v50
	v_mul_f32_e32 v141, 0xbfb8aa3b, v51
	v_mul_f32_e32 v133, 0xbfb8aa3b, v48
	v_mul_f32_e32 v134, 0xbfb8aa3b, v53
	v_exp_f32_e32 v133, v133
	v_exp_f32_e32 v134, v134
	v_mul_f32_e32 v135, 0xbfb8aa3b, v49
	v_exp_f32_e32 v135, v135
	v_add_f32_e32 v133, 1.0, v133
	v_add_f32_e32 v134, 1.0, v134
	v_rcp_f32_e32 v133, v133
	v_rcp_f32_e32 v134, v134
	v_add_f32_e32 v132, 1.0, v140
	v_mul_f32_e32 v140, 0xbfb8aa3b, v55
	v_mul_f32_e32 v138, v48, v133
	v_mul_f32_e32 v133, v53, v134
	v_add_f32_e32 v134, 1.0, v135
	v_mul_f32_e32 v135, 0xbfb8aa3b, v54
	v_exp_f32_e32 v135, v135
	v_exp_f32_e32 v140, v140
	v_exp_f32_e32 v139, v139
	v_exp_f32_e32 v141, v141
	v_add_f32_e32 v135, 1.0, v135
	v_rcp_f32_e32 v132, v132
	v_rcp_f32_e32 v134, v134
	v_rcp_f32_e32 v135, v135
	v_add_f32_e32 v140, 1.0, v140
	v_add_f32_e32 v139, 1.0, v139
	v_rcp_f32_e32 v140, v140
	v_add_f32_e32 v141, 1.0, v141
	v_rcp_f32_e32 v139, v139
	v_rcp_f32_e32 v141, v141
	v_mul_f32_e32 v132, v52, v132
	v_mul_f32_e32 v134, v49, v134
	v_mul_f32_e32 v135, v54, v135
	v_mul_f32_e32 v140, v55, v140
	v_cvt_pk_bf16_f32 v132, v132, v133
	v_cvt_pk_bf16_f32 v133, v135, v140
	v_cvt_pk_bf16_f32 v134, v138, v134
	v_mul_f32_e32 v135, 0xbfb8aa3b, v44
	v_mul_f32_e32 v139, v50, v139
	v_mul_f32_e32 v141, v51, v141
	v_exp_f32_e32 v138, v135
	v_cvt_pk_bf16_f32 v135, v139, v141
	global_store_dwordx4 v[136:137], v[132:135], off offset:64
	v_mul_f32_e32 v140, 0xbfb8aa3b, v47
	v_mul_f32_e32 v139, 0xbfb8aa3b, v42
	v_mul_f32_e32 v133, 0xbfb8aa3b, v40
	v_mul_f32_e32 v134, 0xbfb8aa3b, v45
	v_exp_f32_e32 v133, v133
	v_exp_f32_e32 v134, v134
	v_mul_f32_e32 v135, 0xbfb8aa3b, v41
	v_exp_f32_e32 v135, v135
	v_add_f32_e32 v133, 1.0, v133
	v_add_f32_e32 v134, 1.0, v134
	v_rcp_f32_e32 v133, v133
	v_rcp_f32_e32 v134, v134
	v_add_f32_e32 v132, 1.0, v138
	v_exp_f32_e32 v140, v140
	v_mul_f32_e32 v138, v40, v133
	v_mul_f32_e32 v133, v45, v134
	v_add_f32_e32 v134, 1.0, v135
	v_mul_f32_e32 v135, 0xbfb8aa3b, v46
	v_exp_f32_e32 v135, v135
	v_exp_f32_e32 v139, v139
	v_mul_f32_e32 v141, 0xbfb8aa3b, v43
	v_exp_f32_e32 v141, v141
	v_rcp_f32_e32 v132, v132
	v_rcp_f32_e32 v134, v134
	v_add_f32_e32 v135, 1.0, v135
	v_add_f32_e32 v140, 1.0, v140
	v_rcp_f32_e32 v135, v135
	v_add_f32_e32 v139, 1.0, v139
	v_rcp_f32_e32 v140, v140
	v_rcp_f32_e32 v139, v139
	v_add_f32_e32 v141, 1.0, v141
	v_rcp_f32_e32 v141, v141
	s_mov_b64 s[0:1], 0x24000
	v_mul_f32_e32 v132, v44, v132
	v_mul_f32_e32 v134, v41, v134
	v_lshl_add_u64 v[136:137], v[128:129], 0, s[0:1]
	v_mul_f32_e32 v135, v46, v135
	v_mul_f32_e32 v140, v47, v140
	v_cvt_pk_bf16_f32 v132, v132, v133
	v_cvt_pk_bf16_f32 v133, v135, v140
	v_cvt_pk_bf16_f32 v134, v138, v134
	v_mul_f32_e32 v138, 0xbfb8aa3b, v36
	s_mov_b32 s0, 0x24000
	v_mul_f32_e32 v139, v42, v139
	v_exp_f32_e32 v140, v138
	v_add_co_u32_e32 v138, vcc, s0, v128
	v_mul_f32_e32 v141, v43, v141
	v_cvt_pk_bf16_f32 v135, v139, v141
	s_nop 0
	v_addc_co_u32_e32 v139, vcc, 0, v129, vcc
	global_store_dwordx4 v[138:139], v[132:135], off
	v_mul_f32_e32 v139, 0xbfb8aa3b, v34
	v_mul_f32_e32 v141, 0xbfb8aa3b, v35
	v_mul_f32_e32 v133, 0xbfb8aa3b, v32
	v_mul_f32_e32 v134, 0xbfb8aa3b, v37
	v_exp_f32_e32 v133, v133
	v_exp_f32_e32 v134, v134
	v_mul_f32_e32 v135, 0xbfb8aa3b, v33
	v_exp_f32_e32 v135, v135
	v_add_f32_e32 v133, 1.0, v133
	v_add_f32_e32 v134, 1.0, v134
	v_rcp_f32_e32 v133, v133
	v_rcp_f32_e32 v134, v134
	v_add_f32_e32 v132, 1.0, v140
	v_mul_f32_e32 v140, 0xbfb8aa3b, v39
	v_mul_f32_e32 v138, v32, v133
	v_mul_f32_e32 v133, v37, v134
	v_add_f32_e32 v134, 1.0, v135
	v_mul_f32_e32 v135, 0xbfb8aa3b, v38
	v_exp_f32_e32 v135, v135
	v_exp_f32_e32 v140, v140
	v_exp_f32_e32 v139, v139
	v_exp_f32_e32 v141, v141
	v_add_f32_e32 v135, 1.0, v135
	v_rcp_f32_e32 v132, v132
	v_rcp_f32_e32 v134, v134
	v_rcp_f32_e32 v135, v135
	v_add_f32_e32 v140, 1.0, v140
	v_add_f32_e32 v139, 1.0, v139
	v_rcp_f32_e32 v140, v140
	v_add_f32_e32 v141, 1.0, v141
	v_rcp_f32_e32 v139, v139
	v_rcp_f32_e32 v141, v141
	v_mul_f32_e32 v132, v36, v132
	v_mul_f32_e32 v134, v33, v134
	v_mul_f32_e32 v135, v38, v135
	v_mul_f32_e32 v140, v39, v140
	v_cvt_pk_bf16_f32 v132, v132, v133
	v_cvt_pk_bf16_f32 v133, v135, v140
	v_cvt_pk_bf16_f32 v134, v138, v134
	v_mul_f32_e32 v135, 0xbfb8aa3b, v28
	v_mul_f32_e32 v139, v34, v139
	v_mul_f32_e32 v141, v35, v141
	v_exp_f32_e32 v138, v135
	v_cvt_pk_bf16_f32 v135, v139, v141
	global_store_dwordx4 v[136:137], v[132:135], off offset:64
	v_mul_f32_e32 v140, 0xbfb8aa3b, v31
	v_mul_f32_e32 v139, 0xbfb8aa3b, v26
	v_mul_f32_e32 v133, 0xbfb8aa3b, v24
	v_mul_f32_e32 v134, 0xbfb8aa3b, v29
	v_exp_f32_e32 v133, v133
	v_exp_f32_e32 v134, v134
	v_mul_f32_e32 v135, 0xbfb8aa3b, v25
	v_exp_f32_e32 v135, v135
	v_add_f32_e32 v133, 1.0, v133
	v_add_f32_e32 v134, 1.0, v134
	v_rcp_f32_e32 v133, v133
	v_rcp_f32_e32 v134, v134
	v_add_f32_e32 v132, 1.0, v138
	v_exp_f32_e32 v140, v140
	v_mul_f32_e32 v138, v24, v133
	v_mul_f32_e32 v133, v29, v134
	v_add_f32_e32 v134, 1.0, v135
	v_mul_f32_e32 v135, 0xbfb8aa3b, v30
	v_exp_f32_e32 v135, v135
	v_exp_f32_e32 v139, v139
	v_mul_f32_e32 v141, 0xbfb8aa3b, v27
	v_exp_f32_e32 v141, v141
	v_rcp_f32_e32 v132, v132
	v_rcp_f32_e32 v134, v134
	v_add_f32_e32 v135, 1.0, v135
	v_add_f32_e32 v140, 1.0, v140
	v_rcp_f32_e32 v135, v135
	v_add_f32_e32 v139, 1.0, v139
	v_rcp_f32_e32 v140, v140
	v_rcp_f32_e32 v139, v139
	v_add_f32_e32 v141, 1.0, v141
	v_rcp_f32_e32 v141, v141
	s_mov_b64 s[0:1], 0x28000
	v_mul_f32_e32 v132, v28, v132
	v_mul_f32_e32 v134, v25, v134
	v_lshl_add_u64 v[136:137], v[128:129], 0, s[0:1]
	v_mul_f32_e32 v135, v30, v135
	v_mul_f32_e32 v140, v31, v140
	v_cvt_pk_bf16_f32 v132, v132, v133
	v_cvt_pk_bf16_f32 v133, v135, v140
	v_cvt_pk_bf16_f32 v134, v138, v134
	v_mul_f32_e32 v138, 0xbfb8aa3b, v20
	s_mov_b32 s0, 0x28000
	v_mul_f32_e32 v139, v26, v139
	v_exp_f32_e32 v140, v138
	v_add_co_u32_e32 v138, vcc, s0, v128
	v_mul_f32_e32 v141, v27, v141
	v_cvt_pk_bf16_f32 v135, v139, v141
	s_nop 0
	v_addc_co_u32_e32 v139, vcc, 0, v129, vcc
	global_store_dwordx4 v[138:139], v[132:135], off
	v_mul_f32_e32 v139, 0xbfb8aa3b, v18
	v_mul_f32_e32 v141, 0xbfb8aa3b, v19
	v_mul_f32_e32 v133, 0xbfb8aa3b, v16
	v_mul_f32_e32 v134, 0xbfb8aa3b, v21
	v_exp_f32_e32 v133, v133
	v_exp_f32_e32 v134, v134
	v_mul_f32_e32 v135, 0xbfb8aa3b, v17
	v_exp_f32_e32 v135, v135
	v_add_f32_e32 v133, 1.0, v133
	v_add_f32_e32 v134, 1.0, v134
	v_rcp_f32_e32 v133, v133
	v_rcp_f32_e32 v134, v134
	v_add_f32_e32 v132, 1.0, v140
	v_mul_f32_e32 v140, 0xbfb8aa3b, v23
	v_mul_f32_e32 v138, v16, v133
	v_mul_f32_e32 v133, v21, v134
	v_add_f32_e32 v134, 1.0, v135
	v_mul_f32_e32 v135, 0xbfb8aa3b, v22
	v_exp_f32_e32 v135, v135
	v_exp_f32_e32 v140, v140
	v_exp_f32_e32 v139, v139
	v_exp_f32_e32 v141, v141
	v_add_f32_e32 v135, 1.0, v135
	v_rcp_f32_e32 v132, v132
	v_rcp_f32_e32 v134, v134
	v_rcp_f32_e32 v135, v135
	v_add_f32_e32 v140, 1.0, v140
	v_add_f32_e32 v139, 1.0, v139
	v_rcp_f32_e32 v140, v140
	v_add_f32_e32 v141, 1.0, v141
	v_rcp_f32_e32 v139, v139
	v_rcp_f32_e32 v141, v141
	v_mul_f32_e32 v132, v20, v132
	v_mul_f32_e32 v134, v17, v134
	v_mul_f32_e32 v135, v22, v135
	v_mul_f32_e32 v140, v23, v140
	v_cvt_pk_bf16_f32 v132, v132, v133
	v_cvt_pk_bf16_f32 v133, v135, v140
	v_cvt_pk_bf16_f32 v134, v138, v134
	v_mul_f32_e32 v135, 0xbfb8aa3b, v12
	v_mul_f32_e32 v139, v18, v139
	v_mul_f32_e32 v141, v19, v141
	v_exp_f32_e32 v138, v135
	v_cvt_pk_bf16_f32 v135, v139, v141
	global_store_dwordx4 v[136:137], v[132:135], off offset:64
	v_mul_f32_e32 v140, 0xbfb8aa3b, v15
	v_mul_f32_e32 v139, 0xbfb8aa3b, v10
	v_mul_f32_e32 v133, 0xbfb8aa3b, v8
	v_mul_f32_e32 v134, 0xbfb8aa3b, v13
	v_exp_f32_e32 v133, v133
	v_exp_f32_e32 v134, v134
	v_mul_f32_e32 v135, 0xbfb8aa3b, v9
	v_exp_f32_e32 v135, v135
	v_add_f32_e32 v133, 1.0, v133
	v_add_f32_e32 v134, 1.0, v134
	v_rcp_f32_e32 v133, v133
	v_rcp_f32_e32 v134, v134
	v_add_f32_e32 v132, 1.0, v138
	v_exp_f32_e32 v140, v140
	v_mul_f32_e32 v138, v8, v133
	v_mul_f32_e32 v133, v13, v134
	v_add_f32_e32 v134, 1.0, v135
	v_mul_f32_e32 v135, 0xbfb8aa3b, v14
	v_exp_f32_e32 v135, v135
	v_mul_f32_e32 v141, 0xbfb8aa3b, v11
	v_exp_f32_e32 v139, v139
	v_exp_f32_e32 v141, v141
	v_rcp_f32_e32 v132, v132
	v_add_f32_e32 v135, 1.0, v135
	v_add_f32_e32 v140, 1.0, v140
	v_rcp_f32_e32 v134, v134
	v_rcp_f32_e32 v135, v135
	v_add_f32_e32 v139, 1.0, v139
	v_rcp_f32_e32 v140, v140
	v_add_f32_e32 v141, 1.0, v141
	s_mov_b64 s[0:1], 0x2c000
	v_rcp_f32_e32 v139, v139
	v_rcp_f32_e32 v141, v141
	v_lshl_add_u64 v[136:137], v[128:129], 0, s[0:1]
	s_mov_b32 s0, 0x2c000
	v_mul_f32_e32 v132, v12, v132
	v_add_co_u32_e32 v128, vcc, s0, v128
	v_mul_f32_e32 v134, v9, v134
	v_mul_f32_e32 v135, v14, v135
	v_mul_f32_e32 v140, v15, v140
	v_cvt_pk_bf16_f32 v132, v132, v133
	v_cvt_pk_bf16_f32 v133, v135, v140
	v_addc_co_u32_e32 v129, vcc, 0, v129, vcc
	v_mul_f32_e32 v139, v10, v139
	v_mul_f32_e32 v141, v11, v141
	v_cvt_pk_bf16_f32 v134, v138, v134
	v_cvt_pk_bf16_f32 v135, v139, v141
	global_store_dwordx4 v[128:129], v[132:135], off
	v_mul_f32_e32 v138, 0xbfb8aa3b, v4
	v_exp_f32_e32 v138, v138
	v_mul_f32_e32 v133, 0xbfb8aa3b, v1
	v_exp_f32_e32 v133, v133
	v_mul_f32_e32 v134, 0xbfb8aa3b, v6
	v_mul_f32_e32 v135, 0xbfb8aa3b, v2
	v_exp_f32_e32 v134, v134
	v_add_f32_e32 v133, 1.0, v133
	v_rcp_f32_e32 v133, v133
	v_exp_f32_e32 v135, v135
	v_add_f32_e32 v128, 1.0, v138
	v_mul_f32_e32 v132, 0xbfb8aa3b, v5
	v_mul_f32_e32 v138, v1, v133
	v_add_f32_e32 v133, 1.0, v134
	v_add_f32_e32 v134, 1.0, v135
	v_mul_f32_e32 v135, 0xbfb8aa3b, v7
	v_mul_f32_e32 v139, 0xbfb8aa3b, v3
	v_mul_f32_e32 v129, 0xbfb8aa3b, v0
	v_exp_f32_e32 v132, v132
	v_exp_f32_e32 v135, v135
	v_exp_f32_e32 v139, v139
	v_exp_f32_e32 v129, v129
	v_add_f32_e32 v132, 1.0, v132
	v_add_f32_e32 v135, 1.0, v135
	v_add_f32_e32 v139, 1.0, v139
	v_add_f32_e32 v129, 1.0, v129
	v_rcp_f32_e32 v132, v132
	v_rcp_f32_e32 v133, v133
	v_rcp_f32_e32 v134, v134
	v_rcp_f32_e32 v135, v135
	v_rcp_f32_e32 v139, v139
	v_rcp_f32_e32 v128, v128
	v_rcp_f32_e32 v129, v129
	v_mul_f32_e32 v132, v5, v132
	v_mul_f32_e32 v133, v6, v133
	v_mul_f32_e32 v140, v2, v134
	v_mul_f32_e32 v134, v7, v135
	v_mul_f32_e32 v135, v3, v139
	s_mov_b64 s[0:1], 0
	v_readlane_b32 s49, v247, 8
	v_readlane_b32 s50, v247, 9
	v_readlane_b32 s51, v247, 10
	v_readlane_b32 s52, v247, 11
	v_readlane_b32 s53, v247, 12
	v_readlane_b32 s56, v247, 15
	v_readlane_b32 s57, v247, 16
	v_readlane_b32 s58, v247, 17
	v_readlane_b32 s59, v247, 18
	v_readlane_b32 s60, v247, 19
	v_readlane_b32 s61, v247, 20
	v_readlane_b32 s62, v247, 21
	v_readlane_b32 s63, v247, 22
	v_mul_f32_e32 v128, v4, v128
	v_mul_f32_e32 v129, v0, v129
	v_cvt_pk_bf16_f32 v132, v128, v132
	v_cvt_pk_bf16_f32 v133, v133, v134
	v_cvt_pk_bf16_f32 v134, v129, v138
	v_cvt_pk_bf16_f32 v135, v140, v135
	global_store_dwordx4 v[136:137], v[132:135], off offset:64

.LBB0_291:
	s_waitcnt vmcnt(0)
	v_readlane_b32 s67, v247, 50
	s_mov_b32 s55, s93

.LBB0_898:
	s_and_b64 vcc, exec, s[8:9]
	s_mov_b32 s16, s0
	s_mov_b32 s2, s1
	s_mov_b32 s43, s42
	s_mov_b32 s17, s41
	s_mov_b64 s[10:11], s[20:21]
	v_mov_b32_e32 v128, v202
	v_mov_b32_e32 v190, v200
	s_mov_b64 s[22:23], s[18:19]
	s_mov_b64 s[12:13], s[4:5]
	s_mov_b32 s3, s40
	s_cbranch_vccnz .LBB0_950
	s_cmpk_gt_u32 s30, 0xff
	s_cbranch_scc0 .Lal3_b
	s_barrier
.Lal3_b:
.LBB0_899:
	s_add_i32 s40, s3, 1
	s_mul_hi_u32 s8, s40, 0xaaaaaaab
	s_lshr_b32 s8, s8, 2
	s_mul_i32 s41, s8, -6
	s_add_i32 s41, s41, s40
	s_mul_hi_i32 s9, s8, s66
	s_mul_i32 s8, s8, s66
	s_add_u32 s20, s8, s65
	s_addc_u32 s21, s9, s64
	v_cmp_gt_i64_e64 s[8:9], s[20:21], v[196:197]
	s_and_b64 vcc, exec, s[8:9]
	s_cbranch_vccnz .LBB0_906
	s_ashr_i32 s0, s20, 31
	s_lshr_b32 s0, s0, 29
	s_add_i32 s0, s20, s0
	s_ashr_i32 s1, s0, 3
	s_and_b32 s0, s0, -8
	s_sub_i32 s0, s20, s0
	s_lshr_b32 s4, s0, 31
	s_bitset1_b32 s4, 7
	s_mul_i32 s0, s4, s0
	s_add_i32 s0, s0, s1
	s_ashr_i32 s1, s0, 31
	s_lshr_b32 s1, s1, 27
	s_add_i32 s1, s0, s1
	s_ashr_i32 s4, s1, 5
	s_lshl_b32 s4, s4, 3
	s_sub_i32 s5, 0x100, s4
	s_min_i32 s5, s5, 8
	s_abs_i32 s15, s5
	v_cvt_f32_u32_e32 v0, s15
	s_sub_i32 s18, 0, s15
	s_andn2_b32 s1, s1, 31
	s_sub_i32 s0, s0, s1
	v_rcp_iflag_f32_e32 v0, v0
	s_abs_i32 s14, s0
	s_xor_b32 s1, s0, s5
	s_ashr_i32 s1, s1, 31
	v_mul_f32_e32 v0, 0x4f7ffffe, v0
	v_cvt_u32_f32_e32 v0, v0
	s_nop 0
	v_readfirstlane_b32 s19, v0
	s_mul_i32 s18, s18, s19
	s_mul_hi_u32 s18, s19, s18
	s_add_i32 s19, s19, s18
	s_mul_hi_u32 s18, s14, s19
	s_mul_i32 s19, s18, s15
	s_sub_i32 s14, s14, s19
	s_add_i32 s19, s18, 1
	s_sub_i32 s20, s14, s15
	s_cmp_ge_u32 s14, s15
	s_cselect_b32 s18, s19, s18
	s_cselect_b32 s14, s20, s14
	s_add_i32 s19, s18, 1
	s_cmp_ge_u32 s14, s15
	s_cselect_b32 s14, s19, s18
	s_xor_b32 s14, s14, s1
	s_sub_i32 s42, s14, s1
	s_mul_i32 s1, s42, s5
	s_sub_i32 s0, s0, s1
	s_add_i32 s0, s0, s4
	s_lshr_b32 s20, s41, 1
	s_bitcmp1_b32 s3, 0
	s_cselect_b64 s[4:5], -1, 0
	s_mov_b64 s[14:15], -1
	s_and_b64 vcc, exec, s[4:5]
	s_cbranch_vccz .LBB0_902
	s_cmp_eq_u32 s20, 1
	s_movk_i32 s1, 0xc8
	s_cselect_b32 s1, 0xc0, s1
	s_cmp_gt_u32 s41, 1
	s_cselect_b32 s1, s1, 0xb0
	v_readlane_b32 s4, v248, 0
	v_readlane_b32 s5, v248, 1
	s_add_u32 s4, s4, s1
	s_addc_u32 s5, s5, 0
	s_load_dwordx2 s[4:5], s[4:5], 0x0
	s_ashr_i32 s1, s0, 31
	s_lshl_b64 s[14:15], s[0:1], 18
	v_readlane_b32 s1, v246, 15
	v_readlane_b32 s44, v248, 49
	s_waitcnt lgkmcnt(0)
	s_add_u32 s4, s4, s14
	s_addc_u32 s5, s5, s15
	s_add_i32 s68, s20, s1
	s_lshl_b64 s[14:15], s[68:69], 20
	v_readlane_b32 s48, v248, 53
	v_readlane_b32 s49, v248, 54
	s_add_u32 s18, s48, s14
	v_readlane_b32 s60, v248, 5
	v_readlane_b32 s45, v248, 50
	v_readlane_b32 s46, v248, 51
	v_readlane_b32 s47, v248, 52
	v_readlane_b32 s50, v248, 55
	v_readlane_b32 s51, v248, 56
	v_readlane_b32 s52, v248, 57
	v_readlane_b32 s53, v248, 58
	v_readlane_b32 s54, v248, 59
	v_readlane_b32 s55, v248, 60
	v_readlane_b32 s56, v248, 61
	v_readlane_b32 s57, v248, 62
	v_readlane_b32 s58, v248, 63
	v_readlane_b32 s59, v247, 0
	s_addc_u32 s19, s49, s15
	s_mov_b64 s[14:15], 0

.LBB0_910:
	s_cmpk_gt_u32 s30, 0xff
	s_cbranch_scc1 .Lal3_a
	s_barrier
.Lal3_a:
	v_mov_b32_e32 v203, v188
	s_lshl_b32 s2, s16, 8
	v_readfirstlane_b32 s15, v203
	s_ashr_i32 s3, s15, 2
	s_andn2_b32 s3, s3, 63
	s_add_i32 s3, s3, s2
	v_and_or_b32 v201, v203, 15, s3
	v_lshlrev_b32_e32 v190, 4, v203
	s_bitcmp0_b32 s17, 0
	s_mov_b64 s[2:3], -1
	s_cbranch_scc1 .LBB0_948
	s_ashr_i32 s2, s17, 1
	s_cmp_gt_i32 s2, 0
	s_cselect_b64 s[10:11], -1, 0
	global_load_dwordx4 v[128:131], v190, s[74:75]
	global_load_dwordx4 v[224:227], v190, s[78:79]
	v_add_u32_e32 v223, 0x2000, v190
	global_load_dwordx4 v[140:143], v223, s[74:75]
	global_load_dwordx4 v[184:187], v223, s[78:79]
	v_add_u32_e32 v236, 0x4000, v190
	global_load_dwordx4 v[156:159], v236, s[74:75]
	global_load_dwordx4 v[180:183], v236, s[78:79]
	v_add_u32_e32 v223, 0x6000, v190
	global_load_dwordx4 v[168:171], v223, s[74:75]
	global_load_dwordx4 v[176:179], v223, s[78:79]
	v_add_u32_e32 v236, 0x8000, v190
	global_load_dwordx4 v[164:167], v236, s[74:75]
	global_load_dwordx4 v[172:175], v236, s[78:79]
	v_add_u32_e32 v223, 0xa000, v190
	global_load_dwordx4 v[152:155], v223, s[74:75]
	global_load_dwordx4 v[160:163], v223, s[78:79]
	v_add_u32_e32 v236, 0xc000, v190
	global_load_dwordx4 v[144:147], v236, s[74:75]
	global_load_dwordx4 v[148:151], v236, s[78:79]
	v_add_u32_e32 v223, 0xe000, v190
	global_load_dwordx4 v[132:135], v223, s[74:75]
	global_load_dwordx4 v[136:139], v223, s[78:79]
	v_mul_f32_e32 v124, 0xbfb8aa3b, v124
	v_mul_f32_e32 v125, 0xbfb8aa3b, v125
	v_mul_f32_e32 v126, 0xbfb8aa3b, v126
	v_mul_f32_e32 v127, 0xbfb8aa3b, v127
	v_mul_f32_e32 v120, 0xbfb8aa3b, v120
	v_mul_f32_e32 v121, 0xbfb8aa3b, v121
	v_mul_f32_e32 v122, 0xbfb8aa3b, v122
	v_mul_f32_e32 v123, 0xbfb8aa3b, v123
	v_exp_f32_e32 v124, v124
	v_exp_f32_e32 v125, v125
	v_exp_f32_e32 v126, v126
	v_exp_f32_e32 v127, v127
	v_exp_f32_e32 v120, v120
	v_exp_f32_e32 v121, v121
	v_exp_f32_e32 v122, v122
	v_exp_f32_e32 v123, v123
	v_add_f32_e32 v124, 1.0, v124
	v_add_f32_e32 v125, 1.0, v125
	v_add_f32_e32 v126, 1.0, v126
	v_add_f32_e32 v127, 1.0, v127
	v_add_f32_e32 v120, 1.0, v120
	v_add_f32_e32 v121, 1.0, v121
	v_add_f32_e32 v122, 1.0, v122
	v_add_f32_e32 v123, 1.0, v123
	v_rcp_f32_e32 v124, v124
	v_rcp_f32_e32 v125, v125
	v_rcp_f32_e32 v126, v126
	v_rcp_f32_e32 v127, v127
	v_rcp_f32_e32 v120, v120
	v_rcp_f32_e32 v121, v121
	v_rcp_f32_e32 v122, v122
	v_rcp_f32_e32 v123, v123
	v_mul_f32_e32 v116, 0xbfb8aa3b, v116
	v_mul_f32_e32 v117, 0xbfb8aa3b, v117
	v_mul_f32_e32 v118, 0xbfb8aa3b, v118
	v_mul_f32_e32 v119, 0xbfb8aa3b, v119
	v_mul_f32_e32 v112, 0xbfb8aa3b, v112
	v_mul_f32_e32 v113, 0xbfb8aa3b, v113
	v_mul_f32_e32 v114, 0xbfb8aa3b, v114
	v_mul_f32_e32 v115, 0xbfb8aa3b, v115
	v_exp_f32_e32 v116, v116
	v_exp_f32_e32 v117, v117
	v_exp_f32_e32 v118, v118
	v_exp_f32_e32 v119, v119
	v_exp_f32_e32 v112, v112
	v_exp_f32_e32 v113, v113
	v_exp_f32_e32 v114, v114
	v_exp_f32_e32 v115, v115
	v_add_f32_e32 v116, 1.0, v116
	v_add_f32_e32 v117, 1.0, v117
	v_add_f32_e32 v118, 1.0, v118
	v_add_f32_e32 v119, 1.0, v119
	v_add_f32_e32 v112, 1.0, v112
	v_add_f32_e32 v113, 1.0, v113
	v_add_f32_e32 v114, 1.0, v114
	v_add_f32_e32 v115, 1.0, v115
	v_rcp_f32_e32 v116, v116
	v_rcp_f32_e32 v117, v117
	v_rcp_f32_e32 v118, v118
	v_rcp_f32_e32 v119, v119
	v_rcp_f32_e32 v112, v112
	v_rcp_f32_e32 v113, v113
	v_rcp_f32_e32 v114, v114
	v_rcp_f32_e32 v115, v115
	v_mul_f32_e32 v108, 0xbfb8aa3b, v108
	v_mul_f32_e32 v109, 0xbfb8aa3b, v109
	v_mul_f32_e32 v110, 0xbfb8aa3b, v110
	v_mul_f32_e32 v111, 0xbfb8aa3b, v111
	v_mul_f32_e32 v104, 0xbfb8aa3b, v104
	v_mul_f32_e32 v105, 0xbfb8aa3b, v105
	v_mul_f32_e32 v106, 0xbfb8aa3b, v106
	v_mul_f32_e32 v107, 0xbfb8aa3b, v107
	v_exp_f32_e32 v108, v108
	v_exp_f32_e32 v109, v109
	v_exp_f32_e32 v110, v110
	v_exp_f32_e32 v111, v111
	v_exp_f32_e32 v104, v104
	v_exp_f32_e32 v105, v105
	v_exp_f32_e32 v106, v106
	v_exp_f32_e32 v107, v107
	v_add_f32_e32 v108, 1.0, v108
	v_add_f32_e32 v109, 1.0, v109
	v_add_f32_e32 v110, 1.0, v110
	v_add_f32_e32 v111, 1.0, v111
	v_add_f32_e32 v104, 1.0, v104
	v_add_f32_e32 v105, 1.0, v105
	v_add_f32_e32 v106, 1.0, v106
	v_add_f32_e32 v107, 1.0, v107
	v_rcp_f32_e32 v108, v108
	v_rcp_f32_e32 v109, v109
	v_rcp_f32_e32 v110, v110
	v_rcp_f32_e32 v111, v111
	v_rcp_f32_e32 v104, v104
	v_rcp_f32_e32 v105, v105
	v_rcp_f32_e32 v106, v106
	v_rcp_f32_e32 v107, v107
	v_mul_f32_e32 v100, 0xbfb8aa3b, v100
	v_mul_f32_e32 v101, 0xbfb8aa3b, v101
	v_mul_f32_e32 v102, 0xbfb8aa3b, v102
	v_mul_f32_e32 v103, 0xbfb8aa3b, v103
	v_mul_f32_e32 v96, 0xbfb8aa3b, v96
	v_mul_f32_e32 v97, 0xbfb8aa3b, v97
	v_mul_f32_e32 v98, 0xbfb8aa3b, v98
	v_mul_f32_e32 v99, 0xbfb8aa3b, v99
	v_exp_f32_e32 v100, v100
	v_exp_f32_e32 v101, v101
	v_exp_f32_e32 v102, v102
	v_exp_f32_e32 v103, v103
	v_exp_f32_e32 v96, v96
	v_exp_f32_e32 v97, v97
	v_exp_f32_e32 v98, v98
	v_exp_f32_e32 v99, v99
	v_add_f32_e32 v100, 1.0, v100
	v_add_f32_e32 v101, 1.0, v101
	v_add_f32_e32 v102, 1.0, v102
	v_add_f32_e32 v103, 1.0, v103
	v_add_f32_e32 v96, 1.0, v96
	v_add_f32_e32 v97, 1.0, v97
	v_add_f32_e32 v98, 1.0, v98
	v_add_f32_e32 v99, 1.0, v99
	v_rcp_f32_e32 v100, v100
	v_rcp_f32_e32 v101, v101
	v_rcp_f32_e32 v102, v102
	v_rcp_f32_e32 v103, v103
	v_rcp_f32_e32 v96, v96
	v_rcp_f32_e32 v97, v97
	v_rcp_f32_e32 v98, v98
	v_rcp_f32_e32 v99, v99
	v_mul_f32_e32 v92, 0xbfb8aa3b, v92
	v_mul_f32_e32 v93, 0xbfb8aa3b, v93
	v_mul_f32_e32 v94, 0xbfb8aa3b, v94
	v_mul_f32_e32 v95, 0xbfb8aa3b, v95
	v_mul_f32_e32 v88, 0xbfb8aa3b, v88
	v_mul_f32_e32 v89, 0xbfb8aa3b, v89
	v_mul_f32_e32 v90, 0xbfb8aa3b, v90
	v_mul_f32_e32 v91, 0xbfb8aa3b, v91
	v_exp_f32_e32 v92, v92
	v_exp_f32_e32 v93, v93
	v_exp_f32_e32 v94, v94
	v_exp_f32_e32 v95, v95
	v_exp_f32_e32 v88, v88
	v_exp_f32_e32 v89, v89
	v_exp_f32_e32 v90, v90
	v_exp_f32_e32 v91, v91
	v_add_f32_e32 v92, 1.0, v92
	v_add_f32_e32 v93, 1.0, v93
	v_add_f32_e32 v94, 1.0, v94
	v_add_f32_e32 v95, 1.0, v95
	v_add_f32_e32 v88, 1.0, v88
	v_add_f32_e32 v89, 1.0, v89
	v_add_f32_e32 v90, 1.0, v90
	v_add_f32_e32 v91, 1.0, v91
	v_rcp_f32_e32 v92, v92
	v_rcp_f32_e32 v93, v93
	v_rcp_f32_e32 v94, v94
	v_rcp_f32_e32 v95, v95
	v_rcp_f32_e32 v88, v88
	v_rcp_f32_e32 v89, v89
	v_rcp_f32_e32 v90, v90
	v_rcp_f32_e32 v91, v91
	v_mul_f32_e32 v84, 0xbfb8aa3b, v84
	v_mul_f32_e32 v85, 0xbfb8aa3b, v85
	v_mul_f32_e32 v86, 0xbfb8aa3b, v86
	v_mul_f32_e32 v87, 0xbfb8aa3b, v87
	v_mul_f32_e32 v80, 0xbfb8aa3b, v80
	v_mul_f32_e32 v81, 0xbfb8aa3b, v81
	v_mul_f32_e32 v82, 0xbfb8aa3b, v82
	v_mul_f32_e32 v83, 0xbfb8aa3b, v83
	v_exp_f32_e32 v84, v84
	v_exp_f32_e32 v85, v85
	v_exp_f32_e32 v86, v86
	v_exp_f32_e32 v87, v87
	v_exp_f32_e32 v80, v80
	v_exp_f32_e32 v81, v81
	v_exp_f32_e32 v82, v82
	v_exp_f32_e32 v83, v83
	v_add_f32_e32 v84, 1.0, v84
	v_add_f32_e32 v85, 1.0, v85
	v_add_f32_e32 v86, 1.0, v86
	v_add_f32_e32 v87, 1.0, v87
	v_add_f32_e32 v80, 1.0, v80
	v_add_f32_e32 v81, 1.0, v81
	v_add_f32_e32 v82, 1.0, v82
	v_add_f32_e32 v83, 1.0, v83
	v_rcp_f32_e32 v84, v84
	v_rcp_f32_e32 v85, v85
	v_rcp_f32_e32 v86, v86
	v_rcp_f32_e32 v87, v87
	v_rcp_f32_e32 v80, v80
	v_rcp_f32_e32 v81, v81
	v_rcp_f32_e32 v82, v82
	v_rcp_f32_e32 v83, v83
	v_mul_f32_e32 v76, 0xbfb8aa3b, v76
	v_mul_f32_e32 v77, 0xbfb8aa3b, v77
	v_mul_f32_e32 v78, 0xbfb8aa3b, v78
	v_mul_f32_e32 v79, 0xbfb8aa3b, v79
	v_mul_f32_e32 v72, 0xbfb8aa3b, v72
	v_mul_f32_e32 v73, 0xbfb8aa3b, v73
	v_mul_f32_e32 v74, 0xbfb8aa3b, v74
	v_mul_f32_e32 v75, 0xbfb8aa3b, v75
	v_exp_f32_e32 v76, v76
	v_exp_f32_e32 v77, v77
	v_exp_f32_e32 v78, v78
	v_exp_f32_e32 v79, v79
	v_exp_f32_e32 v72, v72
	v_exp_f32_e32 v73, v73
	v_exp_f32_e32 v74, v74
	v_exp_f32_e32 v75, v75
	v_add_f32_e32 v76, 1.0, v76
	v_add_f32_e32 v77, 1.0, v77
	v_add_f32_e32 v78, 1.0, v78
	v_add_f32_e32 v79, 1.0, v79
	v_add_f32_e32 v72, 1.0, v72
	v_add_f32_e32 v73, 1.0, v73
	v_add_f32_e32 v74, 1.0, v74
	v_add_f32_e32 v75, 1.0, v75
	v_rcp_f32_e32 v76, v76
	v_rcp_f32_e32 v77, v77
	v_rcp_f32_e32 v78, v78
	v_rcp_f32_e32 v79, v79
	v_rcp_f32_e32 v72, v72
	v_rcp_f32_e32 v73, v73
	v_rcp_f32_e32 v74, v74
	v_rcp_f32_e32 v75, v75
	v_mul_f32_e32 v68, 0xbfb8aa3b, v68
	v_mul_f32_e32 v69, 0xbfb8aa3b, v69
	v_mul_f32_e32 v70, 0xbfb8aa3b, v70
	v_mul_f32_e32 v71, 0xbfb8aa3b, v71
	v_mul_f32_e32 v64, 0xbfb8aa3b, v64
	v_mul_f32_e32 v65, 0xbfb8aa3b, v65
	v_mul_f32_e32 v66, 0xbfb8aa3b, v66
	v_mul_f32_e32 v67, 0xbfb8aa3b, v67
	v_exp_f32_e32 v68, v68
	v_exp_f32_e32 v69, v69
	v_exp_f32_e32 v70, v70
	v_exp_f32_e32 v71, v71
	v_exp_f32_e32 v64, v64
	v_exp_f32_e32 v65, v65
	v_exp_f32_e32 v66, v66
	v_exp_f32_e32 v67, v67
	v_add_f32_e32 v68, 1.0, v68
	v_add_f32_e32 v69, 1.0, v69
	v_add_f32_e32 v70, 1.0, v70
	v_add_f32_e32 v71, 1.0, v71
	v_add_f32_e32 v64, 1.0, v64
	v_add_f32_e32 v65, 1.0, v65
	v_add_f32_e32 v66, 1.0, v66
	v_add_f32_e32 v67, 1.0, v67
	v_rcp_f32_e32 v68, v68
	v_rcp_f32_e32 v69, v69
	v_rcp_f32_e32 v70, v70
	v_rcp_f32_e32 v71, v71
	v_rcp_f32_e32 v64, v64
	v_rcp_f32_e32 v65, v65
	v_rcp_f32_e32 v66, v66
	v_rcp_f32_e32 v67, v67
	s_waitcnt vmcnt(14)
	v_cndmask_b32_e64 v224, 0, v224, s[10:11]
	v_cndmask_b32_e64 v225, 0, v225, s[10:11]
	v_cndmask_b32_e64 v226, 0, v226, s[10:11]
	v_cndmask_b32_e64 v227, 0, v227, s[10:11]
	v_lshlrev_b32_e32 v228, 16, v128
	v_lshlrev_b32_e32 v229, 16, v129
	v_lshlrev_b32_e32 v230, 16, v130
	v_lshlrev_b32_e32 v231, 16, v131
	v_lshlrev_b32_e32 v232, 16, v224
	v_lshlrev_b32_e32 v233, 16, v225
	v_lshlrev_b32_e32 v234, 16, v226
	v_lshlrev_b32_e32 v235, 16, v227
	v_and_b32_e32 v128, 0xffff0000, v128
	v_and_b32_e32 v129, 0xffff0000, v129
	v_and_b32_e32 v130, 0xffff0000, v130
	v_and_b32_e32 v131, 0xffff0000, v131
	v_and_b32_e32 v224, 0xffff0000, v224
	v_and_b32_e32 v225, 0xffff0000, v225
	v_and_b32_e32 v226, 0xffff0000, v226
	v_and_b32_e32 v227, 0xffff0000, v227
	v_fmac_f32_e32 v232, v124, v228
	v_fmac_f32_e32 v233, v126, v229
	v_fmac_f32_e32 v234, v120, v230
	v_fmac_f32_e32 v235, v122, v231
	v_fmac_f32_e32 v224, v125, v128
	v_fmac_f32_e32 v225, v127, v129
	v_fmac_f32_e32 v226, v121, v130
	v_fmac_f32_e32 v227, v123, v131
	v_cvt_pk_bf16_f32 v128, v232, v224
	v_cvt_pk_bf16_f32 v129, v233, v225
	v_cvt_pk_bf16_f32 v130, v234, v226
	v_cvt_pk_bf16_f32 v131, v235, v227
	v_add_u32_e32 v236, 0x10000, v190
	global_load_dwordx4 v[124:127], v236, s[74:75]
	global_load_dwordx4 v[120:123], v236, s[78:79]
	s_waitcnt vmcnt(14)
	v_cndmask_b32_e64 v184, 0, v184, s[10:11]
	v_cndmask_b32_e64 v185, 0, v185, s[10:11]
	v_cndmask_b32_e64 v186, 0, v186, s[10:11]
	v_cndmask_b32_e64 v187, 0, v187, s[10:11]
	v_lshlrev_b32_e32 v228, 16, v140
	v_lshlrev_b32_e32 v229, 16, v141
	v_lshlrev_b32_e32 v230, 16, v142
	v_lshlrev_b32_e32 v231, 16, v143
	v_lshlrev_b32_e32 v232, 16, v184
	v_lshlrev_b32_e32 v233, 16, v185
	v_lshlrev_b32_e32 v234, 16, v186
	v_lshlrev_b32_e32 v235, 16, v187
	v_and_b32_e32 v140, 0xffff0000, v140
	v_and_b32_e32 v141, 0xffff0000, v141
	v_and_b32_e32 v142, 0xffff0000, v142
	v_and_b32_e32 v143, 0xffff0000, v143
	v_and_b32_e32 v184, 0xffff0000, v184
	v_and_b32_e32 v185, 0xffff0000, v185
	v_and_b32_e32 v186, 0xffff0000, v186
	v_and_b32_e32 v187, 0xffff0000, v187
	v_fmac_f32_e32 v232, v116, v228
	v_fmac_f32_e32 v233, v118, v229
	v_fmac_f32_e32 v234, v112, v230
	v_fmac_f32_e32 v235, v114, v231
	v_fmac_f32_e32 v184, v117, v140
	v_fmac_f32_e32 v185, v119, v141
	v_fmac_f32_e32 v186, v113, v142
	v_fmac_f32_e32 v187, v115, v143
	v_cvt_pk_bf16_f32 v140, v232, v184
	v_cvt_pk_bf16_f32 v141, v233, v185
	v_cvt_pk_bf16_f32 v142, v234, v186
	v_cvt_pk_bf16_f32 v143, v235, v187
	v_add_u32_e32 v223, 0x12000, v190
	global_load_dwordx4 v[116:119], v223, s[74:75]
	global_load_dwordx4 v[112:115], v223, s[78:79]
	s_waitcnt vmcnt(14)
	v_cndmask_b32_e64 v180, 0, v180, s[10:11]
	v_cndmask_b32_e64 v181, 0, v181, s[10:11]
	v_cndmask_b32_e64 v182, 0, v182, s[10:11]
	v_cndmask_b32_e64 v183, 0, v183, s[10:11]
	v_lshlrev_b32_e32 v228, 16, v156
	v_lshlrev_b32_e32 v229, 16, v157
	v_lshlrev_b32_e32 v230, 16, v158
	v_lshlrev_b32_e32 v231, 16, v159
	v_lshlrev_b32_e32 v232, 16, v180
	v_lshlrev_b32_e32 v233, 16, v181
	v_lshlrev_b32_e32 v234, 16, v182
	v_lshlrev_b32_e32 v235, 16, v183
	v_and_b32_e32 v156, 0xffff0000, v156
	v_and_b32_e32 v157, 0xffff0000, v157
	v_and_b32_e32 v158, 0xffff0000, v158
	v_and_b32_e32 v159, 0xffff0000, v159
	v_and_b32_e32 v180, 0xffff0000, v180
	v_and_b32_e32 v181, 0xffff0000, v181
	v_and_b32_e32 v182, 0xffff0000, v182
	v_and_b32_e32 v183, 0xffff0000, v183
	v_fmac_f32_e32 v232, v108, v228
	v_fmac_f32_e32 v233, v110, v229
	v_fmac_f32_e32 v234, v104, v230
	v_fmac_f32_e32 v235, v106, v231
	v_fmac_f32_e32 v180, v109, v156
	v_fmac_f32_e32 v181, v111, v157
	v_fmac_f32_e32 v182, v105, v158
	v_fmac_f32_e32 v183, v107, v159
	v_cvt_pk_bf16_f32 v156, v232, v180
	v_cvt_pk_bf16_f32 v157, v233, v181
	v_cvt_pk_bf16_f32 v158, v234, v182
	v_cvt_pk_bf16_f32 v159, v235, v183
	v_add_u32_e32 v236, 0x14000, v190
	global_load_dwordx4 v[108:111], v236, s[74:75]
	global_load_dwordx4 v[104:107], v236, s[78:79]
	s_waitcnt vmcnt(14)
	v_cndmask_b32_e64 v176, 0, v176, s[10:11]
	v_cndmask_b32_e64 v177, 0, v177, s[10:11]
	v_cndmask_b32_e64 v178, 0, v178, s[10:11]
	v_cndmask_b32_e64 v179, 0, v179, s[10:11]
	v_lshlrev_b32_e32 v228, 16, v168
	v_lshlrev_b32_e32 v229, 16, v169
	v_lshlrev_b32_e32 v230, 16, v170
	v_lshlrev_b32_e32 v231, 16, v171
	v_lshlrev_b32_e32 v232, 16, v176
	v_lshlrev_b32_e32 v233, 16, v177
	v_lshlrev_b32_e32 v234, 16, v178
	v_lshlrev_b32_e32 v235, 16, v179
	v_and_b32_e32 v168, 0xffff0000, v168
	v_and_b32_e32 v169, 0xffff0000, v169
	v_and_b32_e32 v170, 0xffff0000, v170
	v_and_b32_e32 v171, 0xffff0000, v171
	v_and_b32_e32 v176, 0xffff0000, v176
	v_and_b32_e32 v177, 0xffff0000, v177
	v_and_b32_e32 v178, 0xffff0000, v178
	v_and_b32_e32 v179, 0xffff0000, v179
	v_fmac_f32_e32 v232, v100, v228
	v_fmac_f32_e32 v233, v102, v229
	v_fmac_f32_e32 v234, v96, v230
	v_fmac_f32_e32 v235, v98, v231
	v_fmac_f32_e32 v176, v101, v168
	v_fmac_f32_e32 v177, v103, v169
	v_fmac_f32_e32 v178, v97, v170
	v_fmac_f32_e32 v179, v99, v171
	v_cvt_pk_bf16_f32 v168, v232, v176
	v_cvt_pk_bf16_f32 v169, v233, v177
	v_cvt_pk_bf16_f32 v170, v234, v178
	v_cvt_pk_bf16_f32 v171, v235, v179
	v_add_u32_e32 v223, 0x16000, v190
	global_load_dwordx4 v[100:103], v223, s[74:75]
	global_load_dwordx4 v[96:99], v223, s[78:79]
	s_waitcnt vmcnt(14)
	v_cndmask_b32_e64 v172, 0, v172, s[10:11]
	v_cndmask_b32_e64 v173, 0, v173, s[10:11]
	v_cndmask_b32_e64 v174, 0, v174, s[10:11]
	v_cndmask_b32_e64 v175, 0, v175, s[10:11]
	v_lshlrev_b32_e32 v228, 16, v164
	v_lshlrev_b32_e32 v229, 16, v165
	v_lshlrev_b32_e32 v230, 16, v166
	v_lshlrev_b32_e32 v231, 16, v167
	v_lshlrev_b32_e32 v232, 16, v172
	v_lshlrev_b32_e32 v233, 16, v173
	v_lshlrev_b32_e32 v234, 16, v174
	v_lshlrev_b32_e32 v235, 16, v175
	v_and_b32_e32 v164, 0xffff0000, v164
	v_and_b32_e32 v165, 0xffff0000, v165
	v_and_b32_e32 v166, 0xffff0000, v166
	v_and_b32_e32 v167, 0xffff0000, v167
	v_and_b32_e32 v172, 0xffff0000, v172
	v_and_b32_e32 v173, 0xffff0000, v173
	v_and_b32_e32 v174, 0xffff0000, v174
	v_and_b32_e32 v175, 0xffff0000, v175
	v_fmac_f32_e32 v232, v92, v228
	v_fmac_f32_e32 v233, v94, v229
	v_fmac_f32_e32 v234, v88, v230
	v_fmac_f32_e32 v235, v90, v231
	v_fmac_f32_e32 v172, v93, v164
	v_fmac_f32_e32 v173, v95, v165
	v_fmac_f32_e32 v174, v89, v166
	v_fmac_f32_e32 v175, v91, v167
	v_cvt_pk_bf16_f32 v164, v232, v172
	v_cvt_pk_bf16_f32 v165, v233, v173
	v_cvt_pk_bf16_f32 v166, v234, v174
	v_cvt_pk_bf16_f32 v167, v235, v175
	v_add_u32_e32 v236, 0x18000, v190
	global_load_dwordx4 v[92:95], v236, s[74:75]
	global_load_dwordx4 v[88:91], v236, s[78:79]
	s_waitcnt vmcnt(14)
	v_cndmask_b32_e64 v160, 0, v160, s[10:11]
	v_cndmask_b32_e64 v161, 0, v161, s[10:11]
	v_cndmask_b32_e64 v162, 0, v162, s[10:11]
	v_cndmask_b32_e64 v163, 0, v163, s[10:11]
	v_lshlrev_b32_e32 v228, 16, v152
	v_lshlrev_b32_e32 v229, 16, v153
	v_lshlrev_b32_e32 v230, 16, v154
	v_lshlrev_b32_e32 v231, 16, v155
	v_lshlrev_b32_e32 v232, 16, v160
	v_lshlrev_b32_e32 v233, 16, v161
	v_lshlrev_b32_e32 v234, 16, v162
	v_lshlrev_b32_e32 v235, 16, v163
	v_and_b32_e32 v152, 0xffff0000, v152
	v_and_b32_e32 v153, 0xffff0000, v153
	v_and_b32_e32 v154, 0xffff0000, v154
	v_and_b32_e32 v155, 0xffff0000, v155
	v_and_b32_e32 v160, 0xffff0000, v160
	v_and_b32_e32 v161, 0xffff0000, v161
	v_and_b32_e32 v162, 0xffff0000, v162
	v_and_b32_e32 v163, 0xffff0000, v163
	v_fmac_f32_e32 v232, v84, v228
	v_fmac_f32_e32 v233, v86, v229
	v_fmac_f32_e32 v234, v80, v230
	v_fmac_f32_e32 v235, v82, v231
	v_fmac_f32_e32 v160, v85, v152
	v_fmac_f32_e32 v161, v87, v153
	v_fmac_f32_e32 v162, v81, v154
	v_fmac_f32_e32 v163, v83, v155
	v_cvt_pk_bf16_f32 v152, v232, v160
	v_cvt_pk_bf16_f32 v153, v233, v161
	v_cvt_pk_bf16_f32 v154, v234, v162
	v_cvt_pk_bf16_f32 v155, v235, v163
	v_add_u32_e32 v223, 0x1a000, v190
	global_load_dwordx4 v[84:87], v223, s[74:75]
	global_load_dwordx4 v[80:83], v223, s[78:79]
	s_waitcnt vmcnt(14)
	v_cndmask_b32_e64 v148, 0, v148, s[10:11]
	v_cndmask_b32_e64 v149, 0, v149, s[10:11]
	v_cndmask_b32_e64 v150, 0, v150, s[10:11]
	v_cndmask_b32_e64 v151, 0, v151, s[10:11]
	v_lshlrev_b32_e32 v228, 16, v144
	v_lshlrev_b32_e32 v229, 16, v145
	v_lshlrev_b32_e32 v230, 16, v146
	v_lshlrev_b32_e32 v231, 16, v147
	v_lshlrev_b32_e32 v232, 16, v148
	v_lshlrev_b32_e32 v233, 16, v149
	v_lshlrev_b32_e32 v234, 16, v150
	v_lshlrev_b32_e32 v235, 16, v151
	v_and_b32_e32 v144, 0xffff0000, v144
	v_and_b32_e32 v145, 0xffff0000, v145
	v_and_b32_e32 v146, 0xffff0000, v146
	v_and_b32_e32 v147, 0xffff0000, v147
	v_and_b32_e32 v148, 0xffff0000, v148
	v_and_b32_e32 v149, 0xffff0000, v149
	v_and_b32_e32 v150, 0xffff0000, v150
	v_and_b32_e32 v151, 0xffff0000, v151
	v_fmac_f32_e32 v232, v76, v228
	v_fmac_f32_e32 v233, v78, v229
	v_fmac_f32_e32 v234, v72, v230
	v_fmac_f32_e32 v235, v74, v231
	v_fmac_f32_e32 v148, v77, v144
	v_fmac_f32_e32 v149, v79, v145
	v_fmac_f32_e32 v150, v73, v146
	v_fmac_f32_e32 v151, v75, v147
	v_cvt_pk_bf16_f32 v144, v232, v148
	v_cvt_pk_bf16_f32 v145, v233, v149
	v_cvt_pk_bf16_f32 v146, v234, v150
	v_cvt_pk_bf16_f32 v147, v235, v151
	v_add_u32_e32 v236, 0x1c000, v190
	global_load_dwordx4 v[76:79], v236, s[74:75]
	global_load_dwordx4 v[72:75], v236, s[78:79]
	s_waitcnt vmcnt(14)
	v_cndmask_b32_e64 v136, 0, v136, s[10:11]
	v_cndmask_b32_e64 v137, 0, v137, s[10:11]
	v_cndmask_b32_e64 v138, 0, v138, s[10:11]
	v_cndmask_b32_e64 v139, 0, v139, s[10:11]
	v_lshlrev_b32_e32 v228, 16, v132
	v_lshlrev_b32_e32 v229, 16, v133
	v_lshlrev_b32_e32 v230, 16, v134
	v_lshlrev_b32_e32 v231, 16, v135
	v_lshlrev_b32_e32 v232, 16, v136
	v_lshlrev_b32_e32 v233, 16, v137
	v_lshlrev_b32_e32 v234, 16, v138
	v_lshlrev_b32_e32 v235, 16, v139
	v_and_b32_e32 v132, 0xffff0000, v132
	v_and_b32_e32 v133, 0xffff0000, v133
	v_and_b32_e32 v134, 0xffff0000, v134
	v_and_b32_e32 v135, 0xffff0000, v135
	v_and_b32_e32 v136, 0xffff0000, v136
	v_and_b32_e32 v137, 0xffff0000, v137
	v_and_b32_e32 v138, 0xffff0000, v138
	v_and_b32_e32 v139, 0xffff0000, v139
	v_fmac_f32_e32 v232, v68, v228
	v_fmac_f32_e32 v233, v70, v229
	v_fmac_f32_e32 v234, v64, v230
	v_fmac_f32_e32 v235, v66, v231
	v_fmac_f32_e32 v136, v69, v132
	v_fmac_f32_e32 v137, v71, v133
	v_fmac_f32_e32 v138, v65, v134
	v_fmac_f32_e32 v139, v67, v135
	v_cvt_pk_bf16_f32 v132, v232, v136
	v_cvt_pk_bf16_f32 v133, v233, v137
	v_cvt_pk_bf16_f32 v134, v234, v138
	v_cvt_pk_bf16_f32 v135, v235, v139
	v_add_u32_e32 v223, 0x1e000, v190
	global_load_dwordx4 v[68:71], v223, s[74:75]
	global_load_dwordx4 v[64:67], v223, s[78:79]
	s_cmp_lt_i32 s2, 2
	s_cbranch_scc0 .Lg3_m0
	global_store_dwordx4 v190, v[128:131], s[78:79]
	v_add_u32_e32 v223, 0x2000, v190
	global_store_dwordx4 v223, v[140:143], s[78:79]
	v_add_u32_e32 v236, 0x4000, v190
	global_store_dwordx4 v236, v[156:159], s[78:79]
	v_add_u32_e32 v223, 0x6000, v190
	global_store_dwordx4 v223, v[168:171], s[78:79]
	v_add_u32_e32 v236, 0x8000, v190
	global_store_dwordx4 v236, v[164:167], s[78:79]
	v_add_u32_e32 v223, 0xa000, v190
	global_store_dwordx4 v223, v[152:155], s[78:79]
	v_add_u32_e32 v236, 0xc000, v190
	global_store_dwordx4 v236, v[144:147], s[78:79]
	v_add_u32_e32 v223, 0xe000, v190
	global_store_dwordx4 v223, v[132:135], s[78:79]
	s_branch .Lg3_s0done
.Lg3_m0:
	s_lshl_b32 s3, s16, 8
	s_ashr_i32 s17, s16, 31
	v_subrev_u32_e32 v204, s3, v201
	s_lshl_b64 s[22:23], s[16:17], 19
	v_readlane_b32 s12, v247, 17
	v_readlane_b32 s13, v247, 18
	s_lshr_b32 s3, s15, 1
	s_and_b32 s3, s3, 0x60
	v_lshrrev_b32_e32 v205, 1, v203
	v_lshlrev_b32_e32 v204, 10, v204
	v_and_or_b32 v205, v205, 24, s3
	s_add_u32 s12, s12, s22
	s_addc_u32 s13, s13, s23
	s_lshl_b32 s22, s43, 9
	v_or_b32_e32 v204, v204, v205
	s_add_u32 s12, s12, s22
	s_addc_u32 s13, s13, 0
	v_lshlrev_b32_e32 v204, 1, v204
	v_add_u32_e32 v205, 0x8000, v204
	v_add_u32_e32 v206, 0x10000, v204
	v_add_u32_e32 v207, 0x18000, v204
	global_store_dwordx4 v204, v[128:131], s[12:13]
	global_store_dwordx4 v205, v[140:143], s[12:13]
	global_store_dwordx4 v206, v[156:159], s[12:13]
	global_store_dwordx4 v207, v[168:171], s[12:13]
	global_store_dwordx4 v204, v[164:167], s[12:13] offset:256
	global_store_dwordx4 v205, v[152:155], s[12:13] offset:256
	global_store_dwordx4 v206, v[144:147], s[12:13] offset:256
	global_store_dwordx4 v207, v[132:135], s[12:13] offset:256
.Lg3_s0done:
	v_mul_f32_e32 v60, 0xbfb8aa3b, v60
	v_mul_f32_e32 v61, 0xbfb8aa3b, v61
	v_mul_f32_e32 v62, 0xbfb8aa3b, v62
	v_mul_f32_e32 v63, 0xbfb8aa3b, v63
	v_mul_f32_e32 v56, 0xbfb8aa3b, v56
	v_mul_f32_e32 v57, 0xbfb8aa3b, v57
	v_mul_f32_e32 v58, 0xbfb8aa3b, v58
	v_mul_f32_e32 v59, 0xbfb8aa3b, v59
	v_exp_f32_e32 v60, v60
	v_exp_f32_e32 v61, v61
	v_exp_f32_e32 v62, v62
	v_exp_f32_e32 v63, v63
	v_exp_f32_e32 v56, v56
	v_exp_f32_e32 v57, v57
	v_exp_f32_e32 v58, v58
	v_exp_f32_e32 v59, v59
	v_add_f32_e32 v60, 1.0, v60
	v_add_f32_e32 v61, 1.0, v61
	v_add_f32_e32 v62, 1.0, v62
	v_add_f32_e32 v63, 1.0, v63
	v_add_f32_e32 v56, 1.0, v56
	v_add_f32_e32 v57, 1.0, v57
	v_add_f32_e32 v58, 1.0, v58
	v_add_f32_e32 v59, 1.0, v59
	v_rcp_f32_e32 v60, v60
	v_rcp_f32_e32 v61, v61
	v_rcp_f32_e32 v62, v62
	v_rcp_f32_e32 v63, v63
	v_rcp_f32_e32 v56, v56
	v_rcp_f32_e32 v57, v57
	v_rcp_f32_e32 v58, v58
	v_rcp_f32_e32 v59, v59
	v_mul_f32_e32 v52, 0xbfb8aa3b, v52
	v_mul_f32_e32 v53, 0xbfb8aa3b, v53
	v_mul_f32_e32 v54, 0xbfb8aa3b, v54
	v_mul_f32_e32 v55, 0xbfb8aa3b, v55
	v_mul_f32_e32 v48, 0xbfb8aa3b, v48
	v_mul_f32_e32 v49, 0xbfb8aa3b, v49
	v_mul_f32_e32 v50, 0xbfb8aa3b, v50
	v_mul_f32_e32 v51, 0xbfb8aa3b, v51
	v_exp_f32_e32 v52, v52
	v_exp_f32_e32 v53, v53
	v_exp_f32_e32 v54, v54
	v_exp_f32_e32 v55, v55
	v_exp_f32_e32 v48, v48
	v_exp_f32_e32 v49, v49
	v_exp_f32_e32 v50, v50
	v_exp_f32_e32 v51, v51
	v_add_f32_e32 v52, 1.0, v52
	v_add_f32_e32 v53, 1.0, v53
	v_add_f32_e32 v54, 1.0, v54
	v_add_f32_e32 v55, 1.0, v55
	v_add_f32_e32 v48, 1.0, v48
	v_add_f32_e32 v49, 1.0, v49
	v_add_f32_e32 v50, 1.0, v50
	v_add_f32_e32 v51, 1.0, v51
	v_rcp_f32_e32 v52, v52
	v_rcp_f32_e32 v53, v53
	v_rcp_f32_e32 v54, v54
	v_rcp_f32_e32 v55, v55
	v_rcp_f32_e32 v48, v48
	v_rcp_f32_e32 v49, v49
	v_rcp_f32_e32 v50, v50
	v_rcp_f32_e32 v51, v51
	v_mul_f32_e32 v44, 0xbfb8aa3b, v44
	v_mul_f32_e32 v45, 0xbfb8aa3b, v45
	v_mul_f32_e32 v46, 0xbfb8aa3b, v46
	v_mul_f32_e32 v47, 0xbfb8aa3b, v47
	v_mul_f32_e32 v40, 0xbfb8aa3b, v40
	v_mul_f32_e32 v41, 0xbfb8aa3b, v41
	v_mul_f32_e32 v42, 0xbfb8aa3b, v42
	v_mul_f32_e32 v43, 0xbfb8aa3b, v43
	v_exp_f32_e32 v44, v44
	v_exp_f32_e32 v45, v45
	v_exp_f32_e32 v46, v46
	v_exp_f32_e32 v47, v47
	v_exp_f32_e32 v40, v40
	v_exp_f32_e32 v41, v41
	v_exp_f32_e32 v42, v42
	v_exp_f32_e32 v43, v43
	v_add_f32_e32 v44, 1.0, v44
	v_add_f32_e32 v45, 1.0, v45
	v_add_f32_e32 v46, 1.0, v46
	v_add_f32_e32 v47, 1.0, v47
	v_add_f32_e32 v40, 1.0, v40
	v_add_f32_e32 v41, 1.0, v41
	v_add_f32_e32 v42, 1.0, v42
	v_add_f32_e32 v43, 1.0, v43
	v_rcp_f32_e32 v44, v44
	v_rcp_f32_e32 v45, v45
	v_rcp_f32_e32 v46, v46
	v_rcp_f32_e32 v47, v47
	v_rcp_f32_e32 v40, v40
	v_rcp_f32_e32 v41, v41
	v_rcp_f32_e32 v42, v42
	v_rcp_f32_e32 v43, v43
	v_mul_f32_e32 v36, 0xbfb8aa3b, v36
	v_mul_f32_e32 v37, 0xbfb8aa3b, v37
	v_mul_f32_e32 v38, 0xbfb8aa3b, v38
	v_mul_f32_e32 v39, 0xbfb8aa3b, v39
	v_mul_f32_e32 v32, 0xbfb8aa3b, v32
	v_mul_f32_e32 v33, 0xbfb8aa3b, v33
	v_mul_f32_e32 v34, 0xbfb8aa3b, v34
	v_mul_f32_e32 v35, 0xbfb8aa3b, v35
	v_exp_f32_e32 v36, v36
	v_exp_f32_e32 v37, v37
	v_exp_f32_e32 v38, v38
	v_exp_f32_e32 v39, v39
	v_exp_f32_e32 v32, v32
	v_exp_f32_e32 v33, v33
	v_exp_f32_e32 v34, v34
	v_exp_f32_e32 v35, v35
	v_add_f32_e32 v36, 1.0, v36
	v_add_f32_e32 v37, 1.0, v37
	v_add_f32_e32 v38, 1.0, v38
	v_add_f32_e32 v39, 1.0, v39
	v_add_f32_e32 v32, 1.0, v32
	v_add_f32_e32 v33, 1.0, v33
	v_add_f32_e32 v34, 1.0, v34
	v_add_f32_e32 v35, 1.0, v35
	v_rcp_f32_e32 v36, v36
	v_rcp_f32_e32 v37, v37
	v_rcp_f32_e32 v38, v38
	v_rcp_f32_e32 v39, v39
	v_rcp_f32_e32 v32, v32
	v_rcp_f32_e32 v33, v33
	v_rcp_f32_e32 v34, v34
	v_rcp_f32_e32 v35, v35
	v_mul_f32_e32 v28, 0xbfb8aa3b, v28
	v_mul_f32_e32 v29, 0xbfb8aa3b, v29
	v_mul_f32_e32 v30, 0xbfb8aa3b, v30
	v_mul_f32_e32 v31, 0xbfb8aa3b, v31
	v_mul_f32_e32 v24, 0xbfb8aa3b, v24
	v_mul_f32_e32 v25, 0xbfb8aa3b, v25
	v_mul_f32_e32 v26, 0xbfb8aa3b, v26
	v_mul_f32_e32 v27, 0xbfb8aa3b, v27
	v_exp_f32_e32 v28, v28
	v_exp_f32_e32 v29, v29
	v_exp_f32_e32 v30, v30
	v_exp_f32_e32 v31, v31
	v_exp_f32_e32 v24, v24
	v_exp_f32_e32 v25, v25
	v_exp_f32_e32 v26, v26
	v_exp_f32_e32 v27, v27
	v_add_f32_e32 v28, 1.0, v28
	v_add_f32_e32 v29, 1.0, v29
	v_add_f32_e32 v30, 1.0, v30
	v_add_f32_e32 v31, 1.0, v31
	v_add_f32_e32 v24, 1.0, v24
	v_add_f32_e32 v25, 1.0, v25
	v_add_f32_e32 v26, 1.0, v26
	v_add_f32_e32 v27, 1.0, v27
	v_rcp_f32_e32 v28, v28
	v_rcp_f32_e32 v29, v29
	v_rcp_f32_e32 v30, v30
	v_rcp_f32_e32 v31, v31
	v_rcp_f32_e32 v24, v24
	v_rcp_f32_e32 v25, v25
	v_rcp_f32_e32 v26, v26
	v_rcp_f32_e32 v27, v27
	v_mul_f32_e32 v20, 0xbfb8aa3b, v20
	v_mul_f32_e32 v21, 0xbfb8aa3b, v21
	v_mul_f32_e32 v22, 0xbfb8aa3b, v22
	v_mul_f32_e32 v23, 0xbfb8aa3b, v23
	v_mul_f32_e32 v16, 0xbfb8aa3b, v16
	v_mul_f32_e32 v17, 0xbfb8aa3b, v17
	v_mul_f32_e32 v18, 0xbfb8aa3b, v18
	v_mul_f32_e32 v19, 0xbfb8aa3b, v19
	v_exp_f32_e32 v20, v20
	v_exp_f32_e32 v21, v21
	v_exp_f32_e32 v22, v22
	v_exp_f32_e32 v23, v23
	v_exp_f32_e32 v16, v16
	v_exp_f32_e32 v17, v17
	v_exp_f32_e32 v18, v18
	v_exp_f32_e32 v19, v19
	v_add_f32_e32 v20, 1.0, v20
	v_add_f32_e32 v21, 1.0, v21
	v_add_f32_e32 v22, 1.0, v22
	v_add_f32_e32 v23, 1.0, v23
	v_add_f32_e32 v16, 1.0, v16
	v_add_f32_e32 v17, 1.0, v17
	v_add_f32_e32 v18, 1.0, v18
	v_add_f32_e32 v19, 1.0, v19
	v_rcp_f32_e32 v20, v20
	v_rcp_f32_e32 v21, v21
	v_rcp_f32_e32 v22, v22
	v_rcp_f32_e32 v23, v23
	v_rcp_f32_e32 v16, v16
	v_rcp_f32_e32 v17, v17
	v_rcp_f32_e32 v18, v18
	v_rcp_f32_e32 v19, v19
	v_mul_f32_e32 v12, 0xbfb8aa3b, v12
	v_mul_f32_e32 v13, 0xbfb8aa3b, v13
	v_mul_f32_e32 v14, 0xbfb8aa3b, v14
	v_mul_f32_e32 v15, 0xbfb8aa3b, v15
	v_mul_f32_e32 v8, 0xbfb8aa3b, v8
	v_mul_f32_e32 v9, 0xbfb8aa3b, v9
	v_mul_f32_e32 v10, 0xbfb8aa3b, v10
	v_mul_f32_e32 v11, 0xbfb8aa3b, v11
	v_exp_f32_e32 v12, v12
	v_exp_f32_e32 v13, v13
	v_exp_f32_e32 v14, v14
	v_exp_f32_e32 v15, v15
	v_exp_f32_e32 v8, v8
	v_exp_f32_e32 v9, v9
	v_exp_f32_e32 v10, v10
	v_exp_f32_e32 v11, v11
	v_add_f32_e32 v12, 1.0, v12
	v_add_f32_e32 v13, 1.0, v13
	v_add_f32_e32 v14, 1.0, v14
	v_add_f32_e32 v15, 1.0, v15
	v_add_f32_e32 v8, 1.0, v8
	v_add_f32_e32 v9, 1.0, v9
	v_add_f32_e32 v10, 1.0, v10
	v_add_f32_e32 v11, 1.0, v11
	v_rcp_f32_e32 v12, v12
	v_rcp_f32_e32 v13, v13
	v_rcp_f32_e32 v14, v14
	v_rcp_f32_e32 v15, v15
	v_rcp_f32_e32 v8, v8
	v_rcp_f32_e32 v9, v9
	v_rcp_f32_e32 v10, v10
	v_rcp_f32_e32 v11, v11
	v_mul_f32_e32 v4, 0xbfb8aa3b, v4
	v_mul_f32_e32 v5, 0xbfb8aa3b, v5
	v_mul_f32_e32 v6, 0xbfb8aa3b, v6
	v_mul_f32_e32 v7, 0xbfb8aa3b, v7
	v_mul_f32_e32 v0, 0xbfb8aa3b, v0
	v_mul_f32_e32 v1, 0xbfb8aa3b, v1
	v_mul_f32_e32 v2, 0xbfb8aa3b, v2
	v_mul_f32_e32 v3, 0xbfb8aa3b, v3
	v_exp_f32_e32 v4, v4
	v_exp_f32_e32 v5, v5
	v_exp_f32_e32 v6, v6
	v_exp_f32_e32 v7, v7
	v_exp_f32_e32 v0, v0
	v_exp_f32_e32 v1, v1
	v_exp_f32_e32 v2, v2
	v_exp_f32_e32 v3, v3
	v_add_f32_e32 v4, 1.0, v4
	v_add_f32_e32 v5, 1.0, v5
	v_add_f32_e32 v6, 1.0, v6
	v_add_f32_e32 v7, 1.0, v7
	v_add_f32_e32 v0, 1.0, v0
	v_add_f32_e32 v1, 1.0, v1
	v_add_f32_e32 v2, 1.0, v2
	v_add_f32_e32 v3, 1.0, v3
	v_rcp_f32_e32 v4, v4
	v_rcp_f32_e32 v5, v5
	v_rcp_f32_e32 v6, v6
	v_rcp_f32_e32 v7, v7
	v_rcp_f32_e32 v0, v0
	v_rcp_f32_e32 v1, v1
	v_rcp_f32_e32 v2, v2
	v_rcp_f32_e32 v3, v3
	s_waitcnt vmcnt(22)
	v_cndmask_b32_e64 v120, 0, v120, s[10:11]
	v_cndmask_b32_e64 v121, 0, v121, s[10:11]
	v_cndmask_b32_e64 v122, 0, v122, s[10:11]
	v_cndmask_b32_e64 v123, 0, v123, s[10:11]
	v_lshlrev_b32_e32 v228, 16, v124
	v_lshlrev_b32_e32 v229, 16, v125
	v_lshlrev_b32_e32 v230, 16, v126
	v_lshlrev_b32_e32 v231, 16, v127
	v_lshlrev_b32_e32 v232, 16, v120
	v_lshlrev_b32_e32 v233, 16, v121
	v_lshlrev_b32_e32 v234, 16, v122
	v_lshlrev_b32_e32 v235, 16, v123
	v_and_b32_e32 v124, 0xffff0000, v124
	v_and_b32_e32 v125, 0xffff0000, v125
	v_and_b32_e32 v126, 0xffff0000, v126
	v_and_b32_e32 v127, 0xffff0000, v127
	v_and_b32_e32 v120, 0xffff0000, v120
	v_and_b32_e32 v121, 0xffff0000, v121
	v_and_b32_e32 v122, 0xffff0000, v122
	v_and_b32_e32 v123, 0xffff0000, v123
	v_fmac_f32_e32 v232, v60, v228
	v_fmac_f32_e32 v233, v62, v229
	v_fmac_f32_e32 v234, v56, v230
	v_fmac_f32_e32 v235, v58, v231
	v_fmac_f32_e32 v120, v61, v124
	v_fmac_f32_e32 v121, v63, v125
	v_fmac_f32_e32 v122, v57, v126
	v_fmac_f32_e32 v123, v59, v127
	v_cvt_pk_bf16_f32 v124, v232, v120
	v_cvt_pk_bf16_f32 v125, v233, v121
	v_cvt_pk_bf16_f32 v126, v234, v122
	v_cvt_pk_bf16_f32 v127, v235, v123
	s_cmp_lt_i32 s2, 2
	s_cbranch_scc0 .Lg3_ns0
	v_add_u32_e32 v236, 0x10000, v190
	global_store_dwordx4 v236, v[124:127], s[78:79]
.Lg3_ns0:
	s_waitcnt vmcnt(20)
	v_cndmask_b32_e64 v112, 0, v112, s[10:11]
	v_cndmask_b32_e64 v113, 0, v113, s[10:11]
	v_cndmask_b32_e64 v114, 0, v114, s[10:11]
	v_cndmask_b32_e64 v115, 0, v115, s[10:11]
	v_lshlrev_b32_e32 v228, 16, v116
	v_lshlrev_b32_e32 v229, 16, v117
	v_lshlrev_b32_e32 v230, 16, v118
	v_lshlrev_b32_e32 v231, 16, v119
	v_lshlrev_b32_e32 v232, 16, v112
	v_lshlrev_b32_e32 v233, 16, v113
	v_lshlrev_b32_e32 v234, 16, v114
	v_lshlrev_b32_e32 v235, 16, v115
	v_and_b32_e32 v116, 0xffff0000, v116
	v_and_b32_e32 v117, 0xffff0000, v117
	v_and_b32_e32 v118, 0xffff0000, v118
	v_and_b32_e32 v119, 0xffff0000, v119
	v_and_b32_e32 v112, 0xffff0000, v112
	v_and_b32_e32 v113, 0xffff0000, v113
	v_and_b32_e32 v114, 0xffff0000, v114
	v_and_b32_e32 v115, 0xffff0000, v115
	v_fmac_f32_e32 v232, v52, v228
	v_fmac_f32_e32 v233, v54, v229
	v_fmac_f32_e32 v234, v48, v230
	v_fmac_f32_e32 v235, v50, v231
	v_fmac_f32_e32 v112, v53, v116
	v_fmac_f32_e32 v113, v55, v117
	v_fmac_f32_e32 v114, v49, v118
	v_fmac_f32_e32 v115, v51, v119
	v_cvt_pk_bf16_f32 v116, v232, v112
	v_cvt_pk_bf16_f32 v117, v233, v113
	v_cvt_pk_bf16_f32 v118, v234, v114
	v_cvt_pk_bf16_f32 v119, v235, v115
	s_cmp_lt_i32 s2, 2
	s_cbranch_scc0 .Lg3_ns1
	v_add_u32_e32 v223, 0x12000, v190
	global_store_dwordx4 v223, v[116:119], s[78:79]
.Lg3_ns1:
	s_waitcnt vmcnt(18)
	v_cndmask_b32_e64 v104, 0, v104, s[10:11]
	v_cndmask_b32_e64 v105, 0, v105, s[10:11]
	v_cndmask_b32_e64 v106, 0, v106, s[10:11]
	v_cndmask_b32_e64 v107, 0, v107, s[10:11]
	v_lshlrev_b32_e32 v228, 16, v108
	v_lshlrev_b32_e32 v229, 16, v109
	v_lshlrev_b32_e32 v230, 16, v110
	v_lshlrev_b32_e32 v231, 16, v111
	v_lshlrev_b32_e32 v232, 16, v104
	v_lshlrev_b32_e32 v233, 16, v105
	v_lshlrev_b32_e32 v234, 16, v106
	v_lshlrev_b32_e32 v235, 16, v107
	v_and_b32_e32 v108, 0xffff0000, v108
	v_and_b32_e32 v109, 0xffff0000, v109
	v_and_b32_e32 v110, 0xffff0000, v110
	v_and_b32_e32 v111, 0xffff0000, v111
	v_and_b32_e32 v104, 0xffff0000, v104
	v_and_b32_e32 v105, 0xffff0000, v105
	v_and_b32_e32 v106, 0xffff0000, v106
	v_and_b32_e32 v107, 0xffff0000, v107
	v_fmac_f32_e32 v232, v44, v228
	v_fmac_f32_e32 v233, v46, v229
	v_fmac_f32_e32 v234, v40, v230
	v_fmac_f32_e32 v235, v42, v231
	v_fmac_f32_e32 v104, v45, v108
	v_fmac_f32_e32 v105, v47, v109
	v_fmac_f32_e32 v106, v41, v110
	v_fmac_f32_e32 v107, v43, v111
	v_cvt_pk_bf16_f32 v108, v232, v104
	v_cvt_pk_bf16_f32 v109, v233, v105
	v_cvt_pk_bf16_f32 v110, v234, v106
	v_cvt_pk_bf16_f32 v111, v235, v107
	s_cmp_lt_i32 s2, 2
	s_cbranch_scc0 .Lg3_ns2
	v_add_u32_e32 v236, 0x14000, v190
	global_store_dwordx4 v236, v[108:111], s[78:79]
.Lg3_ns2:
	s_waitcnt vmcnt(16)
	v_cndmask_b32_e64 v96, 0, v96, s[10:11]
	v_cndmask_b32_e64 v97, 0, v97, s[10:11]
	v_cndmask_b32_e64 v98, 0, v98, s[10:11]
	v_cndmask_b32_e64 v99, 0, v99, s[10:11]
	v_lshlrev_b32_e32 v228, 16, v100
	v_lshlrev_b32_e32 v229, 16, v101
	v_lshlrev_b32_e32 v230, 16, v102
	v_lshlrev_b32_e32 v231, 16, v103
	v_lshlrev_b32_e32 v232, 16, v96
	v_lshlrev_b32_e32 v233, 16, v97
	v_lshlrev_b32_e32 v234, 16, v98
	v_lshlrev_b32_e32 v235, 16, v99
	v_and_b32_e32 v100, 0xffff0000, v100
	v_and_b32_e32 v101, 0xffff0000, v101
	v_and_b32_e32 v102, 0xffff0000, v102
	v_and_b32_e32 v103, 0xffff0000, v103
	v_and_b32_e32 v96, 0xffff0000, v96
	v_and_b32_e32 v97, 0xffff0000, v97
	v_and_b32_e32 v98, 0xffff0000, v98
	v_and_b32_e32 v99, 0xffff0000, v99
	v_fmac_f32_e32 v232, v36, v228
	v_fmac_f32_e32 v233, v38, v229
	v_fmac_f32_e32 v234, v32, v230
	v_fmac_f32_e32 v235, v34, v231
	v_fmac_f32_e32 v96, v37, v100
	v_fmac_f32_e32 v97, v39, v101
	v_fmac_f32_e32 v98, v33, v102
	v_fmac_f32_e32 v99, v35, v103
	v_cvt_pk_bf16_f32 v100, v232, v96
	v_cvt_pk_bf16_f32 v101, v233, v97
	v_cvt_pk_bf16_f32 v102, v234, v98
	v_cvt_pk_bf16_f32 v103, v235, v99
	s_cmp_lt_i32 s2, 2
	s_cbranch_scc0 .Lg3_ns3
	v_add_u32_e32 v223, 0x16000, v190
	global_store_dwordx4 v223, v[100:103], s[78:79]
.Lg3_ns3:
	s_waitcnt vmcnt(14)
	v_cndmask_b32_e64 v88, 0, v88, s[10:11]
	v_cndmask_b32_e64 v89, 0, v89, s[10:11]
	v_cndmask_b32_e64 v90, 0, v90, s[10:11]
	v_cndmask_b32_e64 v91, 0, v91, s[10:11]
	v_lshlrev_b32_e32 v228, 16, v92
	v_lshlrev_b32_e32 v229, 16, v93
	v_lshlrev_b32_e32 v230, 16, v94
	v_lshlrev_b32_e32 v231, 16, v95
	v_lshlrev_b32_e32 v232, 16, v88
	v_lshlrev_b32_e32 v233, 16, v89
	v_lshlrev_b32_e32 v234, 16, v90
	v_lshlrev_b32_e32 v235, 16, v91
	v_and_b32_e32 v92, 0xffff0000, v92
	v_and_b32_e32 v93, 0xffff0000, v93
	v_and_b32_e32 v94, 0xffff0000, v94
	v_and_b32_e32 v95, 0xffff0000, v95
	v_and_b32_e32 v88, 0xffff0000, v88
	v_and_b32_e32 v89, 0xffff0000, v89
	v_and_b32_e32 v90, 0xffff0000, v90
	v_and_b32_e32 v91, 0xffff0000, v91
	v_fmac_f32_e32 v232, v28, v228
	v_fmac_f32_e32 v233, v30, v229
	v_fmac_f32_e32 v234, v24, v230
	v_fmac_f32_e32 v235, v26, v231
	v_fmac_f32_e32 v88, v29, v92
	v_fmac_f32_e32 v89, v31, v93
	v_fmac_f32_e32 v90, v25, v94
	v_fmac_f32_e32 v91, v27, v95
	v_cvt_pk_bf16_f32 v92, v232, v88
	v_cvt_pk_bf16_f32 v93, v233, v89
	v_cvt_pk_bf16_f32 v94, v234, v90
	v_cvt_pk_bf16_f32 v95, v235, v91
	s_cmp_lt_i32 s2, 2
	s_cbranch_scc0 .Lg3_ns4
	v_add_u32_e32 v236, 0x18000, v190
	global_store_dwordx4 v236, v[92:95], s[78:79]
.Lg3_ns4:
	s_waitcnt vmcnt(12)
	v_cndmask_b32_e64 v80, 0, v80, s[10:11]
	v_cndmask_b32_e64 v81, 0, v81, s[10:11]
	v_cndmask_b32_e64 v82, 0, v82, s[10:11]
	v_cndmask_b32_e64 v83, 0, v83, s[10:11]
	v_lshlrev_b32_e32 v228, 16, v84
	v_lshlrev_b32_e32 v229, 16, v85
	v_lshlrev_b32_e32 v230, 16, v86
	v_lshlrev_b32_e32 v231, 16, v87
	v_lshlrev_b32_e32 v232, 16, v80
	v_lshlrev_b32_e32 v233, 16, v81
	v_lshlrev_b32_e32 v234, 16, v82
	v_lshlrev_b32_e32 v235, 16, v83
	v_and_b32_e32 v84, 0xffff0000, v84
	v_and_b32_e32 v85, 0xffff0000, v85
	v_and_b32_e32 v86, 0xffff0000, v86
	v_and_b32_e32 v87, 0xffff0000, v87
	v_and_b32_e32 v80, 0xffff0000, v80
	v_and_b32_e32 v81, 0xffff0000, v81
	v_and_b32_e32 v82, 0xffff0000, v82
	v_and_b32_e32 v83, 0xffff0000, v83
	v_fmac_f32_e32 v232, v20, v228
	v_fmac_f32_e32 v233, v22, v229
	v_fmac_f32_e32 v234, v16, v230
	v_fmac_f32_e32 v235, v18, v231
	v_fmac_f32_e32 v80, v21, v84
	v_fmac_f32_e32 v81, v23, v85
	v_fmac_f32_e32 v82, v17, v86
	v_fmac_f32_e32 v83, v19, v87
	v_cvt_pk_bf16_f32 v84, v232, v80
	v_cvt_pk_bf16_f32 v85, v233, v81
	v_cvt_pk_bf16_f32 v86, v234, v82
	v_cvt_pk_bf16_f32 v87, v235, v83
	s_cmp_lt_i32 s2, 2
	s_cbranch_scc0 .Lg3_ns5
	v_add_u32_e32 v223, 0x1a000, v190
	global_store_dwordx4 v223, v[84:87], s[78:79]
.Lg3_ns5:
	s_waitcnt vmcnt(10)
	v_cndmask_b32_e64 v72, 0, v72, s[10:11]
	v_cndmask_b32_e64 v73, 0, v73, s[10:11]
	v_cndmask_b32_e64 v74, 0, v74, s[10:11]
	v_cndmask_b32_e64 v75, 0, v75, s[10:11]
	v_lshlrev_b32_e32 v228, 16, v76
	v_lshlrev_b32_e32 v229, 16, v77
	v_lshlrev_b32_e32 v230, 16, v78
	v_lshlrev_b32_e32 v231, 16, v79
	v_lshlrev_b32_e32 v232, 16, v72
	v_lshlrev_b32_e32 v233, 16, v73
	v_lshlrev_b32_e32 v234, 16, v74
	v_lshlrev_b32_e32 v235, 16, v75
	v_and_b32_e32 v76, 0xffff0000, v76
	v_and_b32_e32 v77, 0xffff0000, v77
	v_and_b32_e32 v78, 0xffff0000, v78
	v_and_b32_e32 v79, 0xffff0000, v79
	v_and_b32_e32 v72, 0xffff0000, v72
	v_and_b32_e32 v73, 0xffff0000, v73
	v_and_b32_e32 v74, 0xffff0000, v74
	v_and_b32_e32 v75, 0xffff0000, v75
	v_fmac_f32_e32 v232, v12, v228
	v_fmac_f32_e32 v233, v14, v229
	v_fmac_f32_e32 v234, v8, v230
	v_fmac_f32_e32 v235, v10, v231
	v_fmac_f32_e32 v72, v13, v76
	v_fmac_f32_e32 v73, v15, v77
	v_fmac_f32_e32 v74, v9, v78
	v_fmac_f32_e32 v75, v11, v79
	v_cvt_pk_bf16_f32 v76, v232, v72
	v_cvt_pk_bf16_f32 v77, v233, v73
	v_cvt_pk_bf16_f32 v78, v234, v74
	v_cvt_pk_bf16_f32 v79, v235, v75
	s_cmp_lt_i32 s2, 2
	s_cbranch_scc0 .Lg3_ns6
	v_add_u32_e32 v236, 0x1c000, v190
	global_store_dwordx4 v236, v[76:79], s[78:79]
.Lg3_ns6:
	s_waitcnt vmcnt(8)
	v_cndmask_b32_e64 v64, 0, v64, s[10:11]
	v_cndmask_b32_e64 v65, 0, v65, s[10:11]
	v_cndmask_b32_e64 v66, 0, v66, s[10:11]
	v_cndmask_b32_e64 v67, 0, v67, s[10:11]
	v_lshlrev_b32_e32 v228, 16, v68
	v_lshlrev_b32_e32 v229, 16, v69
	v_lshlrev_b32_e32 v230, 16, v70
	v_lshlrev_b32_e32 v231, 16, v71
	v_lshlrev_b32_e32 v232, 16, v64
	v_lshlrev_b32_e32 v233, 16, v65
	v_lshlrev_b32_e32 v234, 16, v66
	v_lshlrev_b32_e32 v235, 16, v67
	v_and_b32_e32 v68, 0xffff0000, v68
	v_and_b32_e32 v69, 0xffff0000, v69
	v_and_b32_e32 v70, 0xffff0000, v70
	v_and_b32_e32 v71, 0xffff0000, v71
	v_and_b32_e32 v64, 0xffff0000, v64
	v_and_b32_e32 v65, 0xffff0000, v65
	v_and_b32_e32 v66, 0xffff0000, v66
	v_and_b32_e32 v67, 0xffff0000, v67
	v_fmac_f32_e32 v232, v4, v228
	v_fmac_f32_e32 v233, v6, v229
	v_fmac_f32_e32 v234, v0, v230
	v_fmac_f32_e32 v235, v2, v231
	v_fmac_f32_e32 v64, v5, v68
	v_fmac_f32_e32 v65, v7, v69
	v_fmac_f32_e32 v66, v1, v70
	v_fmac_f32_e32 v67, v3, v71
	v_cvt_pk_bf16_f32 v68, v232, v64
	v_cvt_pk_bf16_f32 v69, v233, v65
	v_cvt_pk_bf16_f32 v70, v234, v66
	v_cvt_pk_bf16_f32 v71, v235, v67
	s_cmp_lt_i32 s2, 2
	s_cbranch_scc0 .Lg3_ns7
	v_add_u32_e32 v223, 0x1e000, v190
	global_store_dwordx4 v223, v[68:71], s[78:79]
.Lg3_ns7:
	s_cmp_lg_u32 s2, 2
	s_cbranch_scc1 .Lg3_end
	v_add_u32_e32 v204, 0x40000, v204
	v_add_u32_e32 v205, 0x40000, v205
	v_add_u32_e32 v206, 0x40000, v206
	v_add_u32_e32 v207, 0x40000, v207
	global_store_dwordx4 v204, v[124:127], s[12:13]
	global_store_dwordx4 v205, v[116:119], s[12:13]
	global_store_dwordx4 v206, v[108:111], s[12:13]
	global_store_dwordx4 v207, v[100:103], s[12:13]
	global_store_dwordx4 v204, v[92:95], s[12:13] offset:256
	global_store_dwordx4 v205, v[84:87], s[12:13] offset:256
	global_store_dwordx4 v206, v[76:79], s[12:13] offset:256
	global_store_dwordx4 v207, v[68:71], s[12:13] offset:256
.Lg3_end:
.LBB0_947:
	s_mov_b64 s[2:3], 0

.LBB0_950:
	s_waitcnt vmcnt(0)
.LBB0_952:
	s_barrier
